# scan waves: forced LDS wait leaves the previous step's first read outstanding (one more step of latency slack), plus V's spread staging bursts
# speedup vs baseline: 1.0214x; 1.0024x over previous
.Lsc_S_loop:
	s_waitcnt lgkmcnt(4)
	v_pk_fma_f32 v[10:11], v[80:81], v[30:31], v[16:17] op_sel_hi:[1,0,1] neg_lo:[0,1,0] neg_hi:[0,1,0]
	v_pk_fma_f32 v[8:9], v[82:83], v[30:31], v[18:19] op_sel_hi:[1,0,1] neg_lo:[0,1,0] neg_hi:[0,1,0]
	v_pk_mul_f32 v[24:25], v[10:11], v[84:85] op_sel:[0,0] op_sel_hi:[0,1]
	v_pk_fma_f32 v[24:25], v[10:11], v[86:87], v[24:25] op_sel:[1,0,0] op_sel_hi:[1,1,1]
	v_pk_fma_f32 v[24:25], v[8:9], v[88:89], v[24:25] op_sel:[0,0,0] op_sel_hi:[0,1,1]
	v_pk_fma_f32 v[24:25], v[8:9], v[90:91], v[24:25] op_sel:[1,0,0] op_sel_hi:[1,1,1]
	v_pk_fma_f32 v[16:17], v[92:93], v[156:157], v[10:11] op_sel:[0,1,0] op_sel_hi:[1,1,1]
	v_pk_fma_f32 v[18:19], v[94:95], v[156:157], v[8:9] op_sel:[0,1,0] op_sel_hi:[1,1,1]
	v_add_f32_dpp v15, v24, v24 row_ror:8 row_mask:0xf bank_mask:0xf bound_ctrl:1
	ds_read_b128 v[124:127], v34 offset:3072
	s_nop 0
	v_add_f32_dpp v15, v15, v15 row_ror:4 row_mask:0xf bank_mask:0xf bound_ctrl:1
	ds_read_b128 v[128:131], v34 offset:3328
	ds_read_b128 v[132:135], v34 offset:3584
	v_add_f32_dpp v15, v15, v15 row_ror:2 row_mask:0xf bank_mask:0xf bound_ctrl:1
	ds_read_b128 v[136:139], v34 offset:3840
	ds_read_b128 v[160:163], v35 offset:16
	v_add_f32_dpp v30, v15, v15 row_ror:1 row_mask:0xf bank_mask:0xf bound_ctrl:1
	v_pk_fma_f32 v[10:11], v[96:97], v[30:31], v[16:17] op_sel_hi:[1,0,1] neg_lo:[0,1,0] neg_hi:[0,1,0]
	v_pk_fma_f32 v[8:9], v[98:99], v[30:31], v[18:19] op_sel_hi:[1,0,1] neg_lo:[0,1,0] neg_hi:[0,1,0]
	v_pk_mul_f32 v[26:27], v[10:11], v[100:101] op_sel:[0,0] op_sel_hi:[0,1]
	v_pk_fma_f32 v[26:27], v[10:11], v[102:103], v[26:27] op_sel:[1,0,0] op_sel_hi:[1,1,1]
	v_pk_fma_f32 v[26:27], v[8:9], v[104:105], v[26:27] op_sel:[0,0,0] op_sel_hi:[0,1,1]
	v_pk_fma_f32 v[26:27], v[8:9], v[106:107], v[26:27] op_sel:[1,0,0] op_sel_hi:[1,1,1]
	s_waitcnt lgkmcnt(8)
	v_pk_fma_f32 v[16:17], v[108:109], v[158:159], v[10:11] op_sel_hi:[1,0,1]
	v_pk_fma_f32 v[18:19], v[110:111], v[158:159], v[8:9] op_sel_hi:[1,0,1]
	v_add_f32_dpp v15, v26, v26 row_ror:8 row_mask:0xf bank_mask:0xf bound_ctrl:1
	ds_read_b128 v[76:79], v34 offset:4096
	s_nop 0
	v_add_f32_dpp v15, v15, v15 row_ror:4 row_mask:0xf bank_mask:0xf bound_ctrl:1
	ds_read_b128 v[80:83], v34 offset:4352
	ds_read_b128 v[84:87], v34 offset:4608
	v_add_f32_dpp v15, v15, v15 row_ror:2 row_mask:0xf bank_mask:0xf bound_ctrl:1
	ds_read_b128 v[88:91], v34 offset:4864
	ds_write2st64_b32 v37, v25, v27 offset0:0 offset1:4
	v_add_f32_dpp v30, v15, v15 row_ror:1 row_mask:0xf bank_mask:0xf bound_ctrl:1
	s_waitcnt lgkmcnt(5)
	v_pk_fma_f32 v[10:11], v[112:113], v[30:31], v[16:17] op_sel_hi:[1,0,1] neg_lo:[0,1,0] neg_hi:[0,1,0]
	v_pk_fma_f32 v[8:9], v[114:115], v[30:31], v[18:19] op_sel_hi:[1,0,1] neg_lo:[0,1,0] neg_hi:[0,1,0]
	v_pk_mul_f32 v[24:25], v[10:11], v[116:117] op_sel:[0,0] op_sel_hi:[0,1]
	v_pk_fma_f32 v[24:25], v[10:11], v[118:119], v[24:25] op_sel:[1,0,0] op_sel_hi:[1,1,1]
	v_pk_fma_f32 v[24:25], v[8:9], v[120:121], v[24:25] op_sel:[0,0,0] op_sel_hi:[0,1,1]
	v_pk_fma_f32 v[24:25], v[8:9], v[122:123], v[24:25] op_sel:[1,0,0] op_sel_hi:[1,1,1]
	v_pk_fma_f32 v[16:17], v[124:125], v[158:159], v[10:11] op_sel:[0,1,0] op_sel_hi:[1,1,1]
	v_pk_fma_f32 v[18:19], v[126:127], v[158:159], v[8:9] op_sel:[0,1,0] op_sel_hi:[1,1,1]
	v_add_f32_dpp v15, v24, v24 row_ror:8 row_mask:0xf bank_mask:0xf bound_ctrl:1
	ds_read_b128 v[92:95], v34 offset:5120
	s_nop 0
	v_add_f32_dpp v15, v15, v15 row_ror:4 row_mask:0xf bank_mask:0xf bound_ctrl:1
	ds_read_b128 v[96:99], v34 offset:5376
	ds_read_b128 v[100:103], v34 offset:5632
	v_add_f32_dpp v15, v15, v15 row_ror:2 row_mask:0xf bank_mask:0xf bound_ctrl:1
	ds_read_b128 v[104:107], v34 offset:5888
	s_nop 0
	v_add_f32_dpp v30, v15, v15 row_ror:1 row_mask:0xf bank_mask:0xf bound_ctrl:1
	v_pk_fma_f32 v[10:11], v[128:129], v[30:31], v[16:17] op_sel_hi:[1,0,1] neg_lo:[0,1,0] neg_hi:[0,1,0]
	v_pk_fma_f32 v[8:9], v[130:131], v[30:31], v[18:19] op_sel_hi:[1,0,1] neg_lo:[0,1,0] neg_hi:[0,1,0]
	v_pk_mul_f32 v[26:27], v[10:11], v[132:133] op_sel:[0,0] op_sel_hi:[0,1]
	v_pk_fma_f32 v[26:27], v[10:11], v[134:135], v[26:27] op_sel:[1,0,0] op_sel_hi:[1,1,1]
	v_pk_fma_f32 v[26:27], v[8:9], v[136:137], v[26:27] op_sel:[0,0,0] op_sel_hi:[0,1,1]
	v_pk_fma_f32 v[26:27], v[8:9], v[138:139], v[26:27] op_sel:[1,0,0] op_sel_hi:[1,1,1]
	s_waitcnt lgkmcnt(8)
	v_pk_fma_f32 v[16:17], v[76:77], v[160:161], v[10:11] op_sel_hi:[1,0,1]
	v_pk_fma_f32 v[18:19], v[78:79], v[160:161], v[8:9] op_sel_hi:[1,0,1]
	v_add_f32_dpp v15, v26, v26 row_ror:8 row_mask:0xf bank_mask:0xf bound_ctrl:1
	ds_read_b128 v[108:111], v34 offset:6144
	s_nop 0
	v_add_f32_dpp v15, v15, v15 row_ror:4 row_mask:0xf bank_mask:0xf bound_ctrl:1
	ds_read_b128 v[112:115], v34 offset:6400
	ds_read_b128 v[116:119], v34 offset:6656
	v_add_f32_dpp v15, v15, v15 row_ror:2 row_mask:0xf bank_mask:0xf bound_ctrl:1
	ds_read_b128 v[120:123], v34 offset:6912
	ds_write2st64_b32 v37, v25, v27 offset0:8 offset1:12
	v_add_f32_dpp v30, v15, v15 row_ror:1 row_mask:0xf bank_mask:0xf bound_ctrl:1
	s_waitcnt lgkmcnt(5)
	v_pk_fma_f32 v[10:11], v[80:81], v[30:31], v[16:17] op_sel_hi:[1,0,1] neg_lo:[0,1,0] neg_hi:[0,1,0]
	v_pk_fma_f32 v[8:9], v[82:83], v[30:31], v[18:19] op_sel_hi:[1,0,1] neg_lo:[0,1,0] neg_hi:[0,1,0]
	v_pk_mul_f32 v[24:25], v[10:11], v[84:85] op_sel:[0,0] op_sel_hi:[0,1]
	v_pk_fma_f32 v[24:25], v[10:11], v[86:87], v[24:25] op_sel:[1,0,0] op_sel_hi:[1,1,1]
	v_pk_fma_f32 v[24:25], v[8:9], v[88:89], v[24:25] op_sel:[0,0,0] op_sel_hi:[0,1,1]
	v_pk_fma_f32 v[24:25], v[8:9], v[90:91], v[24:25] op_sel:[1,0,0] op_sel_hi:[1,1,1]
	v_pk_fma_f32 v[16:17], v[92:93], v[160:161], v[10:11] op_sel:[0,1,0] op_sel_hi:[1,1,1]
	v_pk_fma_f32 v[18:19], v[94:95], v[160:161], v[8:9] op_sel:[0,1,0] op_sel_hi:[1,1,1]
	v_add_f32_dpp v15, v24, v24 row_ror:8 row_mask:0xf bank_mask:0xf bound_ctrl:1
	ds_read_b128 v[124:127], v34 offset:7168
	s_nop 0
	v_add_f32_dpp v15, v15, v15 row_ror:4 row_mask:0xf bank_mask:0xf bound_ctrl:1
	ds_read_b128 v[128:131], v34 offset:7424
	ds_read_b128 v[132:135], v34 offset:7680
	v_add_f32_dpp v15, v15, v15 row_ror:2 row_mask:0xf bank_mask:0xf bound_ctrl:1
	ds_read_b128 v[136:139], v34 offset:7936
	ds_read_b128 v[156:159], v35 offset:32
	v_add_f32_dpp v30, v15, v15 row_ror:1 row_mask:0xf bank_mask:0xf bound_ctrl:1
	v_pk_fma_f32 v[10:11], v[96:97], v[30:31], v[16:17] op_sel_hi:[1,0,1] neg_lo:[0,1,0] neg_hi:[0,1,0]
	v_pk_fma_f32 v[8:9], v[98:99], v[30:31], v[18:19] op_sel_hi:[1,0,1] neg_lo:[0,1,0] neg_hi:[0,1,0]
	v_pk_mul_f32 v[26:27], v[10:11], v[100:101] op_sel:[0,0] op_sel_hi:[0,1]
	v_pk_fma_f32 v[26:27], v[10:11], v[102:103], v[26:27] op_sel:[1,0,0] op_sel_hi:[1,1,1]
	v_pk_fma_f32 v[26:27], v[8:9], v[104:105], v[26:27] op_sel:[0,0,0] op_sel_hi:[0,1,1]
	v_pk_fma_f32 v[26:27], v[8:9], v[106:107], v[26:27] op_sel:[1,0,0] op_sel_hi:[1,1,1]
	s_waitcnt lgkmcnt(9)
	v_pk_fma_f32 v[16:17], v[108:109], v[162:163], v[10:11] op_sel_hi:[1,0,1]
	v_pk_fma_f32 v[18:19], v[110:111], v[162:163], v[8:9] op_sel_hi:[1,0,1]
	v_add_f32_dpp v15, v26, v26 row_ror:8 row_mask:0xf bank_mask:0xf bound_ctrl:1
	ds_read_b128 v[76:79], v34 offset:8192
	s_nop 0
	v_add_f32_dpp v15, v15, v15 row_ror:4 row_mask:0xf bank_mask:0xf bound_ctrl:1
	ds_read_b128 v[80:83], v34 offset:8448
	ds_read_b128 v[84:87], v34 offset:8704
	v_add_f32_dpp v15, v15, v15 row_ror:2 row_mask:0xf bank_mask:0xf bound_ctrl:1
	ds_read_b128 v[88:91], v34 offset:8960
	ds_write2st64_b32 v37, v25, v27 offset0:16 offset1:20
	v_add_f32_dpp v30, v15, v15 row_ror:1 row_mask:0xf bank_mask:0xf bound_ctrl:1
	s_waitcnt lgkmcnt(5)
	v_pk_fma_f32 v[10:11], v[112:113], v[30:31], v[16:17] op_sel_hi:[1,0,1] neg_lo:[0,1,0] neg_hi:[0,1,0]
	v_pk_fma_f32 v[8:9], v[114:115], v[30:31], v[18:19] op_sel_hi:[1,0,1] neg_lo:[0,1,0] neg_hi:[0,1,0]
	v_pk_mul_f32 v[24:25], v[10:11], v[116:117] op_sel:[0,0] op_sel_hi:[0,1]
	v_pk_fma_f32 v[24:25], v[10:11], v[118:119], v[24:25] op_sel:[1,0,0] op_sel_hi:[1,1,1]
	v_pk_fma_f32 v[24:25], v[8:9], v[120:121], v[24:25] op_sel:[0,0,0] op_sel_hi:[0,1,1]
	v_pk_fma_f32 v[24:25], v[8:9], v[122:123], v[24:25] op_sel:[1,0,0] op_sel_hi:[1,1,1]
	v_pk_fma_f32 v[16:17], v[124:125], v[162:163], v[10:11] op_sel:[0,1,0] op_sel_hi:[1,1,1]
	v_pk_fma_f32 v[18:19], v[126:127], v[162:163], v[8:9] op_sel:[0,1,0] op_sel_hi:[1,1,1]
	v_add_f32_dpp v15, v24, v24 row_ror:8 row_mask:0xf bank_mask:0xf bound_ctrl:1
	ds_read_b128 v[92:95], v34 offset:9216
	s_nop 0
	v_add_f32_dpp v15, v15, v15 row_ror:4 row_mask:0xf bank_mask:0xf bound_ctrl:1
	ds_read_b128 v[96:99], v34 offset:9472
	ds_read_b128 v[100:103], v34 offset:9728
	v_add_f32_dpp v15, v15, v15 row_ror:2 row_mask:0xf bank_mask:0xf bound_ctrl:1
	ds_read_b128 v[104:107], v34 offset:9984
	s_nop 0
	v_add_f32_dpp v30, v15, v15 row_ror:1 row_mask:0xf bank_mask:0xf bound_ctrl:1
	v_pk_fma_f32 v[10:11], v[128:129], v[30:31], v[16:17] op_sel_hi:[1,0,1] neg_lo:[0,1,0] neg_hi:[0,1,0]
	v_pk_fma_f32 v[8:9], v[130:131], v[30:31], v[18:19] op_sel_hi:[1,0,1] neg_lo:[0,1,0] neg_hi:[0,1,0]
	v_pk_mul_f32 v[26:27], v[10:11], v[132:133] op_sel:[0,0] op_sel_hi:[0,1]
	v_pk_fma_f32 v[26:27], v[10:11], v[134:135], v[26:27] op_sel:[1,0,0] op_sel_hi:[1,1,1]
	v_pk_fma_f32 v[26:27], v[8:9], v[136:137], v[26:27] op_sel:[0,0,0] op_sel_hi:[0,1,1]
	v_pk_fma_f32 v[26:27], v[8:9], v[138:139], v[26:27] op_sel:[1,0,0] op_sel_hi:[1,1,1]
	s_waitcnt lgkmcnt(8)
	v_pk_fma_f32 v[16:17], v[76:77], v[156:157], v[10:11] op_sel_hi:[1,0,1]
	v_pk_fma_f32 v[18:19], v[78:79], v[156:157], v[8:9] op_sel_hi:[1,0,1]
	v_add_f32_dpp v15, v26, v26 row_ror:8 row_mask:0xf bank_mask:0xf bound_ctrl:1
	ds_read_b128 v[108:111], v34 offset:10240
	s_nop 0
	v_add_f32_dpp v15, v15, v15 row_ror:4 row_mask:0xf bank_mask:0xf bound_ctrl:1
	ds_read_b128 v[112:115], v34 offset:10496
	ds_read_b128 v[116:119], v34 offset:10752
	v_add_f32_dpp v15, v15, v15 row_ror:2 row_mask:0xf bank_mask:0xf bound_ctrl:1
	ds_read_b128 v[120:123], v34 offset:11008
	ds_write2st64_b32 v37, v25, v27 offset0:24 offset1:28
	v_add_f32_dpp v30, v15, v15 row_ror:1 row_mask:0xf bank_mask:0xf bound_ctrl:1
	s_waitcnt lgkmcnt(5)
	v_pk_fma_f32 v[10:11], v[80:81], v[30:31], v[16:17] op_sel_hi:[1,0,1] neg_lo:[0,1,0] neg_hi:[0,1,0]
	v_pk_fma_f32 v[8:9], v[82:83], v[30:31], v[18:19] op_sel_hi:[1,0,1] neg_lo:[0,1,0] neg_hi:[0,1,0]
	v_pk_mul_f32 v[24:25], v[10:11], v[84:85] op_sel:[0,0] op_sel_hi:[0,1]
	v_pk_fma_f32 v[24:25], v[10:11], v[86:87], v[24:25] op_sel:[1,0,0] op_sel_hi:[1,1,1]
	v_pk_fma_f32 v[24:25], v[8:9], v[88:89], v[24:25] op_sel:[0,0,0] op_sel_hi:[0,1,1]
	v_pk_fma_f32 v[24:25], v[8:9], v[90:91], v[24:25] op_sel:[1,0,0] op_sel_hi:[1,1,1]
	v_pk_fma_f32 v[16:17], v[92:93], v[156:157], v[10:11] op_sel:[0,1,0] op_sel_hi:[1,1,1]
	v_pk_fma_f32 v[18:19], v[94:95], v[156:157], v[8:9] op_sel:[0,1,0] op_sel_hi:[1,1,1]
	v_add_f32_dpp v15, v24, v24 row_ror:8 row_mask:0xf bank_mask:0xf bound_ctrl:1
	ds_read_b128 v[124:127], v34 offset:11264
	s_nop 0
	v_add_f32_dpp v15, v15, v15 row_ror:4 row_mask:0xf bank_mask:0xf bound_ctrl:1
	ds_read_b128 v[128:131], v34 offset:11520
	ds_read_b128 v[132:135], v34 offset:11776
	v_add_f32_dpp v15, v15, v15 row_ror:2 row_mask:0xf bank_mask:0xf bound_ctrl:1
	ds_read_b128 v[136:139], v34 offset:12032
	ds_read_b128 v[160:163], v35 offset:48
	v_add_f32_dpp v30, v15, v15 row_ror:1 row_mask:0xf bank_mask:0xf bound_ctrl:1
	v_pk_fma_f32 v[10:11], v[96:97], v[30:31], v[16:17] op_sel_hi:[1,0,1] neg_lo:[0,1,0] neg_hi:[0,1,0]
	v_pk_fma_f32 v[8:9], v[98:99], v[30:31], v[18:19] op_sel_hi:[1,0,1] neg_lo:[0,1,0] neg_hi:[0,1,0]
	v_pk_mul_f32 v[26:27], v[10:11], v[100:101] op_sel:[0,0] op_sel_hi:[0,1]
	v_pk_fma_f32 v[26:27], v[10:11], v[102:103], v[26:27] op_sel:[1,0,0] op_sel_hi:[1,1,1]
	v_pk_fma_f32 v[26:27], v[8:9], v[104:105], v[26:27] op_sel:[0,0,0] op_sel_hi:[0,1,1]
	v_pk_fma_f32 v[26:27], v[8:9], v[106:107], v[26:27] op_sel:[1,0,0] op_sel_hi:[1,1,1]
	s_waitcnt lgkmcnt(9)
	v_pk_fma_f32 v[16:17], v[108:109], v[158:159], v[10:11] op_sel_hi:[1,0,1]
	v_pk_fma_f32 v[18:19], v[110:111], v[158:159], v[8:9] op_sel_hi:[1,0,1]
	v_add_f32_dpp v15, v26, v26 row_ror:8 row_mask:0xf bank_mask:0xf bound_ctrl:1
	ds_read_b128 v[76:79], v34 offset:12288
	s_nop 0
	v_add_f32_dpp v15, v15, v15 row_ror:4 row_mask:0xf bank_mask:0xf bound_ctrl:1
	ds_read_b128 v[80:83], v34 offset:12544
	ds_read_b128 v[84:87], v34 offset:12800
	v_add_f32_dpp v15, v15, v15 row_ror:2 row_mask:0xf bank_mask:0xf bound_ctrl:1
	ds_read_b128 v[88:91], v34 offset:13056
	ds_write2st64_b32 v37, v25, v27 offset0:32 offset1:36
	v_add_f32_dpp v30, v15, v15 row_ror:1 row_mask:0xf bank_mask:0xf bound_ctrl:1
	s_waitcnt lgkmcnt(5)
	v_pk_fma_f32 v[10:11], v[112:113], v[30:31], v[16:17] op_sel_hi:[1,0,1] neg_lo:[0,1,0] neg_hi:[0,1,0]
	v_pk_fma_f32 v[8:9], v[114:115], v[30:31], v[18:19] op_sel_hi:[1,0,1] neg_lo:[0,1,0] neg_hi:[0,1,0]
	v_pk_mul_f32 v[24:25], v[10:11], v[116:117] op_sel:[0,0] op_sel_hi:[0,1]
	v_pk_fma_f32 v[24:25], v[10:11], v[118:119], v[24:25] op_sel:[1,0,0] op_sel_hi:[1,1,1]
	v_pk_fma_f32 v[24:25], v[8:9], v[120:121], v[24:25] op_sel:[0,0,0] op_sel_hi:[0,1,1]
	v_pk_fma_f32 v[24:25], v[8:9], v[122:123], v[24:25] op_sel:[1,0,0] op_sel_hi:[1,1,1]
	v_pk_fma_f32 v[16:17], v[124:125], v[158:159], v[10:11] op_sel:[0,1,0] op_sel_hi:[1,1,1]
	v_pk_fma_f32 v[18:19], v[126:127], v[158:159], v[8:9] op_sel:[0,1,0] op_sel_hi:[1,1,1]
	v_add_f32_dpp v15, v24, v24 row_ror:8 row_mask:0xf bank_mask:0xf bound_ctrl:1
	ds_read_b128 v[92:95], v34 offset:13312
	s_nop 0
	v_add_f32_dpp v15, v15, v15 row_ror:4 row_mask:0xf bank_mask:0xf bound_ctrl:1
	ds_read_b128 v[96:99], v34 offset:13568
	ds_read_b128 v[100:103], v34 offset:13824
	v_add_f32_dpp v15, v15, v15 row_ror:2 row_mask:0xf bank_mask:0xf bound_ctrl:1
	ds_read_b128 v[104:107], v34 offset:14080
	s_nop 0
	v_add_f32_dpp v30, v15, v15 row_ror:1 row_mask:0xf bank_mask:0xf bound_ctrl:1
	v_pk_fma_f32 v[10:11], v[128:129], v[30:31], v[16:17] op_sel_hi:[1,0,1] neg_lo:[0,1,0] neg_hi:[0,1,0]
	v_pk_fma_f32 v[8:9], v[130:131], v[30:31], v[18:19] op_sel_hi:[1,0,1] neg_lo:[0,1,0] neg_hi:[0,1,0]
	v_pk_mul_f32 v[26:27], v[10:11], v[132:133] op_sel:[0,0] op_sel_hi:[0,1]
	v_pk_fma_f32 v[26:27], v[10:11], v[134:135], v[26:27] op_sel:[1,0,0] op_sel_hi:[1,1,1]
	v_pk_fma_f32 v[26:27], v[8:9], v[136:137], v[26:27] op_sel:[0,0,0] op_sel_hi:[0,1,1]
	v_pk_fma_f32 v[26:27], v[8:9], v[138:139], v[26:27] op_sel:[1,0,0] op_sel_hi:[1,1,1]
	s_waitcnt lgkmcnt(8)
	v_pk_fma_f32 v[16:17], v[76:77], v[160:161], v[10:11] op_sel_hi:[1,0,1]
	v_pk_fma_f32 v[18:19], v[78:79], v[160:161], v[8:9] op_sel_hi:[1,0,1]
	v_add_f32_dpp v15, v26, v26 row_ror:8 row_mask:0xf bank_mask:0xf bound_ctrl:1
	ds_read_b128 v[108:111], v34 offset:14336
	s_nop 0
	v_add_f32_dpp v15, v15, v15 row_ror:4 row_mask:0xf bank_mask:0xf bound_ctrl:1
	ds_read_b128 v[112:115], v34 offset:14592
	ds_read_b128 v[116:119], v34 offset:14848
	v_add_f32_dpp v15, v15, v15 row_ror:2 row_mask:0xf bank_mask:0xf bound_ctrl:1
	ds_read_b128 v[120:123], v34 offset:15104
	ds_write2st64_b32 v37, v25, v27 offset0:40 offset1:44
	v_add_f32_dpp v30, v15, v15 row_ror:1 row_mask:0xf bank_mask:0xf bound_ctrl:1
	s_waitcnt lgkmcnt(5)
	v_pk_fma_f32 v[10:11], v[80:81], v[30:31], v[16:17] op_sel_hi:[1,0,1] neg_lo:[0,1,0] neg_hi:[0,1,0]
	v_pk_fma_f32 v[8:9], v[82:83], v[30:31], v[18:19] op_sel_hi:[1,0,1] neg_lo:[0,1,0] neg_hi:[0,1,0]
	v_pk_mul_f32 v[24:25], v[10:11], v[84:85] op_sel:[0,0] op_sel_hi:[0,1]
	v_pk_fma_f32 v[24:25], v[10:11], v[86:87], v[24:25] op_sel:[1,0,0] op_sel_hi:[1,1,1]
	v_pk_fma_f32 v[24:25], v[8:9], v[88:89], v[24:25] op_sel:[0,0,0] op_sel_hi:[0,1,1]
	v_pk_fma_f32 v[24:25], v[8:9], v[90:91], v[24:25] op_sel:[1,0,0] op_sel_hi:[1,1,1]
	v_pk_fma_f32 v[16:17], v[92:93], v[160:161], v[10:11] op_sel:[0,1,0] op_sel_hi:[1,1,1]
	v_pk_fma_f32 v[18:19], v[94:95], v[160:161], v[8:9] op_sel:[0,1,0] op_sel_hi:[1,1,1]
	v_add_f32_dpp v15, v24, v24 row_ror:8 row_mask:0xf bank_mask:0xf bound_ctrl:1
	ds_read_b128 v[124:127], v34 offset:15360
	s_nop 0
	v_add_f32_dpp v15, v15, v15 row_ror:4 row_mask:0xf bank_mask:0xf bound_ctrl:1
	ds_read_b128 v[128:131], v34 offset:15616
	ds_read_b128 v[132:135], v34 offset:15872
	v_add_f32_dpp v15, v15, v15 row_ror:2 row_mask:0xf bank_mask:0xf bound_ctrl:1
	ds_read_b128 v[136:139], v34 offset:16128
	ds_read_b128 v[156:159], v35 offset:64
	v_add_f32_dpp v30, v15, v15 row_ror:1 row_mask:0xf bank_mask:0xf bound_ctrl:1
	v_pk_fma_f32 v[10:11], v[96:97], v[30:31], v[16:17] op_sel_hi:[1,0,1] neg_lo:[0,1,0] neg_hi:[0,1,0]
	v_pk_fma_f32 v[8:9], v[98:99], v[30:31], v[18:19] op_sel_hi:[1,0,1] neg_lo:[0,1,0] neg_hi:[0,1,0]
	v_pk_mul_f32 v[26:27], v[10:11], v[100:101] op_sel:[0,0] op_sel_hi:[0,1]
	v_pk_fma_f32 v[26:27], v[10:11], v[102:103], v[26:27] op_sel:[1,0,0] op_sel_hi:[1,1,1]
	v_pk_fma_f32 v[26:27], v[8:9], v[104:105], v[26:27] op_sel:[0,0,0] op_sel_hi:[0,1,1]
	v_pk_fma_f32 v[26:27], v[8:9], v[106:107], v[26:27] op_sel:[1,0,0] op_sel_hi:[1,1,1]
	s_waitcnt lgkmcnt(9)
	v_pk_fma_f32 v[16:17], v[108:109], v[162:163], v[10:11] op_sel_hi:[1,0,1]
	v_pk_fma_f32 v[18:19], v[110:111], v[162:163], v[8:9] op_sel_hi:[1,0,1]
	v_add_f32_dpp v15, v26, v26 row_ror:8 row_mask:0xf bank_mask:0xf bound_ctrl:1
	ds_read_b128 v[76:79], v34 offset:16384
	s_nop 0
	v_add_f32_dpp v15, v15, v15 row_ror:4 row_mask:0xf bank_mask:0xf bound_ctrl:1
	ds_read_b128 v[80:83], v34 offset:16640
	ds_read_b128 v[84:87], v34 offset:16896
	v_add_f32_dpp v15, v15, v15 row_ror:2 row_mask:0xf bank_mask:0xf bound_ctrl:1
	ds_read_b128 v[88:91], v34 offset:17152
	ds_write2st64_b32 v37, v25, v27 offset0:48 offset1:52
	v_add_f32_dpp v30, v15, v15 row_ror:1 row_mask:0xf bank_mask:0xf bound_ctrl:1
	s_waitcnt lgkmcnt(5)
	v_pk_fma_f32 v[10:11], v[112:113], v[30:31], v[16:17] op_sel_hi:[1,0,1] neg_lo:[0,1,0] neg_hi:[0,1,0]
	v_pk_fma_f32 v[8:9], v[114:115], v[30:31], v[18:19] op_sel_hi:[1,0,1] neg_lo:[0,1,0] neg_hi:[0,1,0]
	v_pk_mul_f32 v[24:25], v[10:11], v[116:117] op_sel:[0,0] op_sel_hi:[0,1]
	v_pk_fma_f32 v[24:25], v[10:11], v[118:119], v[24:25] op_sel:[1,0,0] op_sel_hi:[1,1,1]
	v_pk_fma_f32 v[24:25], v[8:9], v[120:121], v[24:25] op_sel:[0,0,0] op_sel_hi:[0,1,1]
	v_pk_fma_f32 v[24:25], v[8:9], v[122:123], v[24:25] op_sel:[1,0,0] op_sel_hi:[1,1,1]
	v_pk_fma_f32 v[16:17], v[124:125], v[162:163], v[10:11] op_sel:[0,1,0] op_sel_hi:[1,1,1]
	v_pk_fma_f32 v[18:19], v[126:127], v[162:163], v[8:9] op_sel:[0,1,0] op_sel_hi:[1,1,1]
	v_add_f32_dpp v15, v24, v24 row_ror:8 row_mask:0xf bank_mask:0xf bound_ctrl:1
	ds_read_b128 v[92:95], v34 offset:17408
	s_nop 0
	v_add_f32_dpp v15, v15, v15 row_ror:4 row_mask:0xf bank_mask:0xf bound_ctrl:1
	ds_read_b128 v[96:99], v34 offset:17664
	ds_read_b128 v[100:103], v34 offset:17920
	v_add_f32_dpp v15, v15, v15 row_ror:2 row_mask:0xf bank_mask:0xf bound_ctrl:1
	ds_read_b128 v[104:107], v34 offset:18176
	s_nop 0
	v_add_f32_dpp v30, v15, v15 row_ror:1 row_mask:0xf bank_mask:0xf bound_ctrl:1
	v_pk_fma_f32 v[10:11], v[128:129], v[30:31], v[16:17] op_sel_hi:[1,0,1] neg_lo:[0,1,0] neg_hi:[0,1,0]
	v_pk_fma_f32 v[8:9], v[130:131], v[30:31], v[18:19] op_sel_hi:[1,0,1] neg_lo:[0,1,0] neg_hi:[0,1,0]
	v_pk_mul_f32 v[26:27], v[10:11], v[132:133] op_sel:[0,0] op_sel_hi:[0,1]
	v_pk_fma_f32 v[26:27], v[10:11], v[134:135], v[26:27] op_sel:[1,0,0] op_sel_hi:[1,1,1]
	v_pk_fma_f32 v[26:27], v[8:9], v[136:137], v[26:27] op_sel:[0,0,0] op_sel_hi:[0,1,1]
	v_pk_fma_f32 v[26:27], v[8:9], v[138:139], v[26:27] op_sel:[1,0,0] op_sel_hi:[1,1,1]
	s_waitcnt lgkmcnt(8)
	v_pk_fma_f32 v[16:17], v[76:77], v[156:157], v[10:11] op_sel_hi:[1,0,1]
	v_pk_fma_f32 v[18:19], v[78:79], v[156:157], v[8:9] op_sel_hi:[1,0,1]
	v_add_f32_dpp v15, v26, v26 row_ror:8 row_mask:0xf bank_mask:0xf bound_ctrl:1
	ds_read_b128 v[108:111], v34 offset:18432
	s_nop 0
	v_add_f32_dpp v15, v15, v15 row_ror:4 row_mask:0xf bank_mask:0xf bound_ctrl:1
	ds_read_b128 v[112:115], v34 offset:18688
	ds_read_b128 v[116:119], v34 offset:18944
	v_add_f32_dpp v15, v15, v15 row_ror:2 row_mask:0xf bank_mask:0xf bound_ctrl:1
	ds_read_b128 v[120:123], v34 offset:19200
	ds_write2st64_b32 v37, v25, v27 offset0:56 offset1:60
	v_add_f32_dpp v30, v15, v15 row_ror:1 row_mask:0xf bank_mask:0xf bound_ctrl:1
	s_waitcnt lgkmcnt(5)
	v_pk_fma_f32 v[10:11], v[80:81], v[30:31], v[16:17] op_sel_hi:[1,0,1] neg_lo:[0,1,0] neg_hi:[0,1,0]
	v_pk_fma_f32 v[8:9], v[82:83], v[30:31], v[18:19] op_sel_hi:[1,0,1] neg_lo:[0,1,0] neg_hi:[0,1,0]
	v_pk_mul_f32 v[24:25], v[10:11], v[84:85] op_sel:[0,0] op_sel_hi:[0,1]
	v_pk_fma_f32 v[24:25], v[10:11], v[86:87], v[24:25] op_sel:[1,0,0] op_sel_hi:[1,1,1]
	v_pk_fma_f32 v[24:25], v[8:9], v[88:89], v[24:25] op_sel:[0,0,0] op_sel_hi:[0,1,1]
	v_pk_fma_f32 v[24:25], v[8:9], v[90:91], v[24:25] op_sel:[1,0,0] op_sel_hi:[1,1,1]
	v_pk_fma_f32 v[16:17], v[92:93], v[156:157], v[10:11] op_sel:[0,1,0] op_sel_hi:[1,1,1]
	v_pk_fma_f32 v[18:19], v[94:95], v[156:157], v[8:9] op_sel:[0,1,0] op_sel_hi:[1,1,1]
	v_add_f32_dpp v15, v24, v24 row_ror:8 row_mask:0xf bank_mask:0xf bound_ctrl:1
	ds_read_b128 v[124:127], v34 offset:19456
	s_nop 0
	v_add_f32_dpp v15, v15, v15 row_ror:4 row_mask:0xf bank_mask:0xf bound_ctrl:1
	ds_read_b128 v[128:131], v34 offset:19712
	ds_read_b128 v[132:135], v34 offset:19968
	v_add_f32_dpp v15, v15, v15 row_ror:2 row_mask:0xf bank_mask:0xf bound_ctrl:1
	ds_read_b128 v[136:139], v34 offset:20224
	ds_read_b128 v[160:163], v35 offset:80
	v_add_f32_dpp v30, v15, v15 row_ror:1 row_mask:0xf bank_mask:0xf bound_ctrl:1
	v_pk_fma_f32 v[10:11], v[96:97], v[30:31], v[16:17] op_sel_hi:[1,0,1] neg_lo:[0,1,0] neg_hi:[0,1,0]
	v_pk_fma_f32 v[8:9], v[98:99], v[30:31], v[18:19] op_sel_hi:[1,0,1] neg_lo:[0,1,0] neg_hi:[0,1,0]
	v_pk_mul_f32 v[26:27], v[10:11], v[100:101] op_sel:[0,0] op_sel_hi:[0,1]
	v_pk_fma_f32 v[26:27], v[10:11], v[102:103], v[26:27] op_sel:[1,0,0] op_sel_hi:[1,1,1]
	v_pk_fma_f32 v[26:27], v[8:9], v[104:105], v[26:27] op_sel:[0,0,0] op_sel_hi:[0,1,1]
	v_pk_fma_f32 v[26:27], v[8:9], v[106:107], v[26:27] op_sel:[1,0,0] op_sel_hi:[1,1,1]
	s_waitcnt lgkmcnt(9)
	v_pk_fma_f32 v[16:17], v[108:109], v[158:159], v[10:11] op_sel_hi:[1,0,1]
	v_pk_fma_f32 v[18:19], v[110:111], v[158:159], v[8:9] op_sel_hi:[1,0,1]
	v_add_f32_dpp v15, v26, v26 row_ror:8 row_mask:0xf bank_mask:0xf bound_ctrl:1
	ds_read_b128 v[76:79], v34 offset:20480
	s_nop 0
	v_add_f32_dpp v15, v15, v15 row_ror:4 row_mask:0xf bank_mask:0xf bound_ctrl:1
	ds_read_b128 v[80:83], v34 offset:20736
	ds_read_b128 v[84:87], v34 offset:20992
	v_add_f32_dpp v15, v15, v15 row_ror:2 row_mask:0xf bank_mask:0xf bound_ctrl:1
	ds_read_b128 v[88:91], v34 offset:21248
	ds_write2st64_b32 v37, v25, v27 offset0:64 offset1:68
	v_add_f32_dpp v30, v15, v15 row_ror:1 row_mask:0xf bank_mask:0xf bound_ctrl:1
	s_waitcnt lgkmcnt(5)
	v_pk_fma_f32 v[10:11], v[112:113], v[30:31], v[16:17] op_sel_hi:[1,0,1] neg_lo:[0,1,0] neg_hi:[0,1,0]
	v_pk_fma_f32 v[8:9], v[114:115], v[30:31], v[18:19] op_sel_hi:[1,0,1] neg_lo:[0,1,0] neg_hi:[0,1,0]
	v_pk_mul_f32 v[24:25], v[10:11], v[116:117] op_sel:[0,0] op_sel_hi:[0,1]
	v_pk_fma_f32 v[24:25], v[10:11], v[118:119], v[24:25] op_sel:[1,0,0] op_sel_hi:[1,1,1]
	v_pk_fma_f32 v[24:25], v[8:9], v[120:121], v[24:25] op_sel:[0,0,0] op_sel_hi:[0,1,1]
	v_pk_fma_f32 v[24:25], v[8:9], v[122:123], v[24:25] op_sel:[1,0,0] op_sel_hi:[1,1,1]
	v_pk_fma_f32 v[16:17], v[124:125], v[158:159], v[10:11] op_sel:[0,1,0] op_sel_hi:[1,1,1]
	v_pk_fma_f32 v[18:19], v[126:127], v[158:159], v[8:9] op_sel:[0,1,0] op_sel_hi:[1,1,1]
	v_add_f32_dpp v15, v24, v24 row_ror:8 row_mask:0xf bank_mask:0xf bound_ctrl:1
	ds_read_b128 v[92:95], v34 offset:21504
	s_nop 0
	v_add_f32_dpp v15, v15, v15 row_ror:4 row_mask:0xf bank_mask:0xf bound_ctrl:1
	ds_read_b128 v[96:99], v34 offset:21760
	ds_read_b128 v[100:103], v34 offset:22016
	v_add_f32_dpp v15, v15, v15 row_ror:2 row_mask:0xf bank_mask:0xf bound_ctrl:1
	ds_read_b128 v[104:107], v34 offset:22272
	s_nop 0
	v_add_f32_dpp v30, v15, v15 row_ror:1 row_mask:0xf bank_mask:0xf bound_ctrl:1
	v_pk_fma_f32 v[10:11], v[128:129], v[30:31], v[16:17] op_sel_hi:[1,0,1] neg_lo:[0,1,0] neg_hi:[0,1,0]
	v_pk_fma_f32 v[8:9], v[130:131], v[30:31], v[18:19] op_sel_hi:[1,0,1] neg_lo:[0,1,0] neg_hi:[0,1,0]
	v_pk_mul_f32 v[26:27], v[10:11], v[132:133] op_sel:[0,0] op_sel_hi:[0,1]
	v_pk_fma_f32 v[26:27], v[10:11], v[134:135], v[26:27] op_sel:[1,0,0] op_sel_hi:[1,1,1]
	v_pk_fma_f32 v[26:27], v[8:9], v[136:137], v[26:27] op_sel:[0,0,0] op_sel_hi:[0,1,1]
	v_pk_fma_f32 v[26:27], v[8:9], v[138:139], v[26:27] op_sel:[1,0,0] op_sel_hi:[1,1,1]
	s_waitcnt lgkmcnt(8)
	v_pk_fma_f32 v[16:17], v[76:77], v[160:161], v[10:11] op_sel_hi:[1,0,1]
	v_pk_fma_f32 v[18:19], v[78:79], v[160:161], v[8:9] op_sel_hi:[1,0,1]
	v_add_f32_dpp v15, v26, v26 row_ror:8 row_mask:0xf bank_mask:0xf bound_ctrl:1
	ds_read_b128 v[108:111], v34 offset:22528
	s_nop 0
	v_add_f32_dpp v15, v15, v15 row_ror:4 row_mask:0xf bank_mask:0xf bound_ctrl:1
	ds_read_b128 v[112:115], v34 offset:22784
	ds_read_b128 v[116:119], v34 offset:23040
	v_add_f32_dpp v15, v15, v15 row_ror:2 row_mask:0xf bank_mask:0xf bound_ctrl:1
	ds_read_b128 v[120:123], v34 offset:23296
	ds_write2st64_b32 v37, v25, v27 offset0:72 offset1:76
	v_add_f32_dpp v30, v15, v15 row_ror:1 row_mask:0xf bank_mask:0xf bound_ctrl:1
	s_waitcnt lgkmcnt(5)
	v_pk_fma_f32 v[10:11], v[80:81], v[30:31], v[16:17] op_sel_hi:[1,0,1] neg_lo:[0,1,0] neg_hi:[0,1,0]
	v_pk_fma_f32 v[8:9], v[82:83], v[30:31], v[18:19] op_sel_hi:[1,0,1] neg_lo:[0,1,0] neg_hi:[0,1,0]
	v_pk_mul_f32 v[24:25], v[10:11], v[84:85] op_sel:[0,0] op_sel_hi:[0,1]
	v_pk_fma_f32 v[24:25], v[10:11], v[86:87], v[24:25] op_sel:[1,0,0] op_sel_hi:[1,1,1]
	v_pk_fma_f32 v[24:25], v[8:9], v[88:89], v[24:25] op_sel:[0,0,0] op_sel_hi:[0,1,1]
	v_pk_fma_f32 v[24:25], v[8:9], v[90:91], v[24:25] op_sel:[1,0,0] op_sel_hi:[1,1,1]
	v_pk_fma_f32 v[16:17], v[92:93], v[160:161], v[10:11] op_sel:[0,1,0] op_sel_hi:[1,1,1]
	v_pk_fma_f32 v[18:19], v[94:95], v[160:161], v[8:9] op_sel:[0,1,0] op_sel_hi:[1,1,1]
	v_add_f32_dpp v15, v24, v24 row_ror:8 row_mask:0xf bank_mask:0xf bound_ctrl:1
	ds_read_b128 v[124:127], v34 offset:23552
	s_nop 0
	v_add_f32_dpp v15, v15, v15 row_ror:4 row_mask:0xf bank_mask:0xf bound_ctrl:1
	ds_read_b128 v[128:131], v34 offset:23808
	ds_read_b128 v[132:135], v34 offset:24064
	v_add_f32_dpp v15, v15, v15 row_ror:2 row_mask:0xf bank_mask:0xf bound_ctrl:1
	ds_read_b128 v[136:139], v34 offset:24320
	ds_read_b128 v[156:159], v35 offset:96
	v_add_f32_dpp v30, v15, v15 row_ror:1 row_mask:0xf bank_mask:0xf bound_ctrl:1
	v_pk_fma_f32 v[10:11], v[96:97], v[30:31], v[16:17] op_sel_hi:[1,0,1] neg_lo:[0,1,0] neg_hi:[0,1,0]
	v_pk_fma_f32 v[8:9], v[98:99], v[30:31], v[18:19] op_sel_hi:[1,0,1] neg_lo:[0,1,0] neg_hi:[0,1,0]
	v_pk_mul_f32 v[26:27], v[10:11], v[100:101] op_sel:[0,0] op_sel_hi:[0,1]
	v_pk_fma_f32 v[26:27], v[10:11], v[102:103], v[26:27] op_sel:[1,0,0] op_sel_hi:[1,1,1]
	v_pk_fma_f32 v[26:27], v[8:9], v[104:105], v[26:27] op_sel:[0,0,0] op_sel_hi:[0,1,1]
	v_pk_fma_f32 v[26:27], v[8:9], v[106:107], v[26:27] op_sel:[1,0,0] op_sel_hi:[1,1,1]
	s_waitcnt lgkmcnt(9)
	v_pk_fma_f32 v[16:17], v[108:109], v[162:163], v[10:11] op_sel_hi:[1,0,1]
	v_pk_fma_f32 v[18:19], v[110:111], v[162:163], v[8:9] op_sel_hi:[1,0,1]
	v_add_f32_dpp v15, v26, v26 row_ror:8 row_mask:0xf bank_mask:0xf bound_ctrl:1
	ds_read_b128 v[76:79], v34 offset:24576
	s_nop 0
	v_add_f32_dpp v15, v15, v15 row_ror:4 row_mask:0xf bank_mask:0xf bound_ctrl:1
	ds_read_b128 v[80:83], v34 offset:24832
	ds_read_b128 v[84:87], v34 offset:25088
	v_add_f32_dpp v15, v15, v15 row_ror:2 row_mask:0xf bank_mask:0xf bound_ctrl:1
	ds_read_b128 v[88:91], v34 offset:25344
	ds_write2st64_b32 v37, v25, v27 offset0:80 offset1:84
	v_add_f32_dpp v30, v15, v15 row_ror:1 row_mask:0xf bank_mask:0xf bound_ctrl:1
	s_waitcnt lgkmcnt(5)
	v_pk_fma_f32 v[10:11], v[112:113], v[30:31], v[16:17] op_sel_hi:[1,0,1] neg_lo:[0,1,0] neg_hi:[0,1,0]
	v_pk_fma_f32 v[8:9], v[114:115], v[30:31], v[18:19] op_sel_hi:[1,0,1] neg_lo:[0,1,0] neg_hi:[0,1,0]
	v_pk_mul_f32 v[24:25], v[10:11], v[116:117] op_sel:[0,0] op_sel_hi:[0,1]
	v_pk_fma_f32 v[24:25], v[10:11], v[118:119], v[24:25] op_sel:[1,0,0] op_sel_hi:[1,1,1]
	v_pk_fma_f32 v[24:25], v[8:9], v[120:121], v[24:25] op_sel:[0,0,0] op_sel_hi:[0,1,1]
	v_pk_fma_f32 v[24:25], v[8:9], v[122:123], v[24:25] op_sel:[1,0,0] op_sel_hi:[1,1,1]
	v_pk_fma_f32 v[16:17], v[124:125], v[162:163], v[10:11] op_sel:[0,1,0] op_sel_hi:[1,1,1]
	v_pk_fma_f32 v[18:19], v[126:127], v[162:163], v[8:9] op_sel:[0,1,0] op_sel_hi:[1,1,1]
	v_add_f32_dpp v15, v24, v24 row_ror:8 row_mask:0xf bank_mask:0xf bound_ctrl:1
	ds_read_b128 v[92:95], v34 offset:25600
	s_nop 0
	v_add_f32_dpp v15, v15, v15 row_ror:4 row_mask:0xf bank_mask:0xf bound_ctrl:1
	ds_read_b128 v[96:99], v34 offset:25856
	ds_read_b128 v[100:103], v34 offset:26112
	v_add_f32_dpp v15, v15, v15 row_ror:2 row_mask:0xf bank_mask:0xf bound_ctrl:1
	ds_read_b128 v[104:107], v34 offset:26368
	s_nop 0
	v_add_f32_dpp v30, v15, v15 row_ror:1 row_mask:0xf bank_mask:0xf bound_ctrl:1
	v_pk_fma_f32 v[10:11], v[128:129], v[30:31], v[16:17] op_sel_hi:[1,0,1] neg_lo:[0,1,0] neg_hi:[0,1,0]
	v_pk_fma_f32 v[8:9], v[130:131], v[30:31], v[18:19] op_sel_hi:[1,0,1] neg_lo:[0,1,0] neg_hi:[0,1,0]
	v_pk_mul_f32 v[26:27], v[10:11], v[132:133] op_sel:[0,0] op_sel_hi:[0,1]
	v_pk_fma_f32 v[26:27], v[10:11], v[134:135], v[26:27] op_sel:[1,0,0] op_sel_hi:[1,1,1]
	v_pk_fma_f32 v[26:27], v[8:9], v[136:137], v[26:27] op_sel:[0,0,0] op_sel_hi:[0,1,1]
	v_pk_fma_f32 v[26:27], v[8:9], v[138:139], v[26:27] op_sel:[1,0,0] op_sel_hi:[1,1,1]
	s_waitcnt lgkmcnt(8)
	v_pk_fma_f32 v[16:17], v[76:77], v[156:157], v[10:11] op_sel_hi:[1,0,1]
	v_pk_fma_f32 v[18:19], v[78:79], v[156:157], v[8:9] op_sel_hi:[1,0,1]
	v_add_f32_dpp v15, v26, v26 row_ror:8 row_mask:0xf bank_mask:0xf bound_ctrl:1
	ds_read_b128 v[108:111], v34 offset:26624
	s_nop 0
	v_add_f32_dpp v15, v15, v15 row_ror:4 row_mask:0xf bank_mask:0xf bound_ctrl:1
	ds_read_b128 v[112:115], v34 offset:26880
	ds_read_b128 v[116:119], v34 offset:27136
	v_add_f32_dpp v15, v15, v15 row_ror:2 row_mask:0xf bank_mask:0xf bound_ctrl:1
	ds_read_b128 v[120:123], v34 offset:27392
	ds_write2st64_b32 v37, v25, v27 offset0:88 offset1:92
	v_add_f32_dpp v30, v15, v15 row_ror:1 row_mask:0xf bank_mask:0xf bound_ctrl:1
	s_waitcnt lgkmcnt(5)
	v_pk_fma_f32 v[10:11], v[80:81], v[30:31], v[16:17] op_sel_hi:[1,0,1] neg_lo:[0,1,0] neg_hi:[0,1,0]
	v_pk_fma_f32 v[8:9], v[82:83], v[30:31], v[18:19] op_sel_hi:[1,0,1] neg_lo:[0,1,0] neg_hi:[0,1,0]
	v_pk_mul_f32 v[24:25], v[10:11], v[84:85] op_sel:[0,0] op_sel_hi:[0,1]
	v_pk_fma_f32 v[24:25], v[10:11], v[86:87], v[24:25] op_sel:[1,0,0] op_sel_hi:[1,1,1]
	v_pk_fma_f32 v[24:25], v[8:9], v[88:89], v[24:25] op_sel:[0,0,0] op_sel_hi:[0,1,1]
	v_pk_fma_f32 v[24:25], v[8:9], v[90:91], v[24:25] op_sel:[1,0,0] op_sel_hi:[1,1,1]
	v_pk_fma_f32 v[16:17], v[92:93], v[156:157], v[10:11] op_sel:[0,1,0] op_sel_hi:[1,1,1]
	v_pk_fma_f32 v[18:19], v[94:95], v[156:157], v[8:9] op_sel:[0,1,0] op_sel_hi:[1,1,1]
	v_add_f32_dpp v15, v24, v24 row_ror:8 row_mask:0xf bank_mask:0xf bound_ctrl:1
	ds_read_b128 v[124:127], v34 offset:27648
	s_nop 0
	v_add_f32_dpp v15, v15, v15 row_ror:4 row_mask:0xf bank_mask:0xf bound_ctrl:1
	ds_read_b128 v[128:131], v34 offset:27904
	ds_read_b128 v[132:135], v34 offset:28160
	v_add_f32_dpp v15, v15, v15 row_ror:2 row_mask:0xf bank_mask:0xf bound_ctrl:1
	ds_read_b128 v[136:139], v34 offset:28416
	ds_read_b128 v[160:163], v35 offset:112
	v_add_f32_dpp v30, v15, v15 row_ror:1 row_mask:0xf bank_mask:0xf bound_ctrl:1
	v_pk_fma_f32 v[10:11], v[96:97], v[30:31], v[16:17] op_sel_hi:[1,0,1] neg_lo:[0,1,0] neg_hi:[0,1,0]
	v_pk_fma_f32 v[8:9], v[98:99], v[30:31], v[18:19] op_sel_hi:[1,0,1] neg_lo:[0,1,0] neg_hi:[0,1,0]
	v_pk_mul_f32 v[26:27], v[10:11], v[100:101] op_sel:[0,0] op_sel_hi:[0,1]
	v_pk_fma_f32 v[26:27], v[10:11], v[102:103], v[26:27] op_sel:[1,0,0] op_sel_hi:[1,1,1]
	v_pk_fma_f32 v[26:27], v[8:9], v[104:105], v[26:27] op_sel:[0,0,0] op_sel_hi:[0,1,1]
	v_pk_fma_f32 v[26:27], v[8:9], v[106:107], v[26:27] op_sel:[1,0,0] op_sel_hi:[1,1,1]
	s_waitcnt lgkmcnt(9)
	v_pk_fma_f32 v[16:17], v[108:109], v[158:159], v[10:11] op_sel_hi:[1,0,1]
	v_pk_fma_f32 v[18:19], v[110:111], v[158:159], v[8:9] op_sel_hi:[1,0,1]
	v_add_f32_dpp v15, v26, v26 row_ror:8 row_mask:0xf bank_mask:0xf bound_ctrl:1
	ds_read_b128 v[76:79], v34 offset:28672
	s_nop 0
	v_add_f32_dpp v15, v15, v15 row_ror:4 row_mask:0xf bank_mask:0xf bound_ctrl:1
	ds_read_b128 v[80:83], v34 offset:28928
	ds_read_b128 v[84:87], v34 offset:29184
	v_add_f32_dpp v15, v15, v15 row_ror:2 row_mask:0xf bank_mask:0xf bound_ctrl:1
	ds_read_b128 v[88:91], v34 offset:29440
	ds_write2st64_b32 v37, v25, v27 offset0:96 offset1:100
	v_add_f32_dpp v30, v15, v15 row_ror:1 row_mask:0xf bank_mask:0xf bound_ctrl:1
	ds_read_b128 v[56:59], v52
	s_waitcnt lgkmcnt(6)
	v_pk_fma_f32 v[10:11], v[112:113], v[30:31], v[16:17] op_sel_hi:[1,0,1] neg_lo:[0,1,0] neg_hi:[0,1,0]
	v_pk_fma_f32 v[8:9], v[114:115], v[30:31], v[18:19] op_sel_hi:[1,0,1] neg_lo:[0,1,0] neg_hi:[0,1,0]
	v_pk_mul_f32 v[24:25], v[10:11], v[116:117] op_sel:[0,0] op_sel_hi:[0,1]
	v_pk_fma_f32 v[24:25], v[10:11], v[118:119], v[24:25] op_sel:[1,0,0] op_sel_hi:[1,1,1]
	v_pk_fma_f32 v[24:25], v[8:9], v[120:121], v[24:25] op_sel:[0,0,0] op_sel_hi:[0,1,1]
	v_pk_fma_f32 v[24:25], v[8:9], v[122:123], v[24:25] op_sel:[1,0,0] op_sel_hi:[1,1,1]
	v_pk_fma_f32 v[16:17], v[124:125], v[158:159], v[10:11] op_sel:[0,1,0] op_sel_hi:[1,1,1]
	v_pk_fma_f32 v[18:19], v[126:127], v[158:159], v[8:9] op_sel:[0,1,0] op_sel_hi:[1,1,1]
	v_add_f32_dpp v15, v24, v24 row_ror:8 row_mask:0xf bank_mask:0xf bound_ctrl:1
	ds_read_b128 v[92:95], v34 offset:29696
	s_nop 0
	v_add_f32_dpp v15, v15, v15 row_ror:4 row_mask:0xf bank_mask:0xf bound_ctrl:1
	ds_read_b128 v[96:99], v34 offset:29952
	ds_read_b128 v[100:103], v34 offset:30208
	v_add_f32_dpp v15, v15, v15 row_ror:2 row_mask:0xf bank_mask:0xf bound_ctrl:1
	ds_read_b128 v[104:107], v34 offset:30464
	s_nop 0
	v_add_f32_dpp v30, v15, v15 row_ror:1 row_mask:0xf bank_mask:0xf bound_ctrl:1
	s_waitcnt lgkmcnt(4)
	v_min_u32_e32 v56, v56, v57
	v_min3_u32 v56, v56, v58, v59
	v_pk_fma_f32 v[10:11], v[128:129], v[30:31], v[16:17] op_sel_hi:[1,0,1] neg_lo:[0,1,0] neg_hi:[0,1,0]
	v_pk_fma_f32 v[8:9], v[130:131], v[30:31], v[18:19] op_sel_hi:[1,0,1] neg_lo:[0,1,0] neg_hi:[0,1,0]
	v_pk_mul_f32 v[26:27], v[10:11], v[132:133] op_sel:[0,0] op_sel_hi:[0,1]
	v_pk_fma_f32 v[26:27], v[10:11], v[134:135], v[26:27] op_sel:[1,0,0] op_sel_hi:[1,1,1]
	v_pk_fma_f32 v[26:27], v[8:9], v[136:137], v[26:27] op_sel:[0,0,0] op_sel_hi:[0,1,1]
	v_pk_fma_f32 v[26:27], v[8:9], v[138:139], v[26:27] op_sel:[1,0,0] op_sel_hi:[1,1,1]
	v_pk_fma_f32 v[16:17], v[76:77], v[160:161], v[10:11] op_sel_hi:[1,0,1]
	v_pk_fma_f32 v[18:19], v[78:79], v[160:161], v[8:9] op_sel_hi:[1,0,1]
	v_add_f32_dpp v15, v26, v26 row_ror:8 row_mask:0xf bank_mask:0xf bound_ctrl:1
	ds_read_b128 v[108:111], v34 offset:30720
	s_nop 0
	v_add_f32_dpp v15, v15, v15 row_ror:4 row_mask:0xf bank_mask:0xf bound_ctrl:1
	ds_read_b128 v[112:115], v34 offset:30976
	ds_read_b128 v[116:119], v34 offset:31232
	v_add_f32_dpp v15, v15, v15 row_ror:2 row_mask:0xf bank_mask:0xf bound_ctrl:1
	ds_read_b128 v[120:123], v34 offset:31488
	ds_read_b128 v[140:143], v34 offset:34560
	ds_write2st64_b32 v37, v25, v27 offset0:104 offset1:108
	v_add_f32_dpp v30, v15, v15 row_ror:1 row_mask:0xf bank_mask:0xf bound_ctrl:1
	s_waitcnt lgkmcnt(6)
	v_pk_fma_f32 v[10:11], v[80:81], v[30:31], v[16:17] op_sel_hi:[1,0,1] neg_lo:[0,1,0] neg_hi:[0,1,0]
	v_pk_fma_f32 v[8:9], v[82:83], v[30:31], v[18:19] op_sel_hi:[1,0,1] neg_lo:[0,1,0] neg_hi:[0,1,0]
	v_pk_mul_f32 v[24:25], v[10:11], v[84:85] op_sel:[0,0] op_sel_hi:[0,1]
	v_pk_fma_f32 v[24:25], v[10:11], v[86:87], v[24:25] op_sel:[1,0,0] op_sel_hi:[1,1,1]
	v_pk_fma_f32 v[24:25], v[8:9], v[88:89], v[24:25] op_sel:[0,0,0] op_sel_hi:[0,1,1]
	v_pk_fma_f32 v[24:25], v[8:9], v[90:91], v[24:25] op_sel:[1,0,0] op_sel_hi:[1,1,1]
	v_pk_fma_f32 v[16:17], v[92:93], v[160:161], v[10:11] op_sel:[0,1,0] op_sel_hi:[1,1,1]
	v_pk_fma_f32 v[18:19], v[94:95], v[160:161], v[8:9] op_sel:[0,1,0] op_sel_hi:[1,1,1]
	v_add_f32_dpp v15, v24, v24 row_ror:8 row_mask:0xf bank_mask:0xf bound_ctrl:1
	ds_read_b128 v[124:127], v34 offset:31744
	s_nop 0
	v_add_f32_dpp v15, v15, v15 row_ror:4 row_mask:0xf bank_mask:0xf bound_ctrl:1
	ds_read_b128 v[128:131], v34 offset:32000
	ds_read_b128 v[132:135], v34 offset:32256
	v_add_f32_dpp v15, v15, v15 row_ror:2 row_mask:0xf bank_mask:0xf bound_ctrl:1
	ds_read_b128 v[136:139], v34 offset:32512
	s_nop 0
	v_add_f32_dpp v30, v15, v15 row_ror:1 row_mask:0xf bank_mask:0xf bound_ctrl:1
	v_readfirstlane_b32 s54, v56
	s_add_u32 s64, s6, 2
	s_cmp_lt_u32 s54, s64
	s_cbranch_scc1 .Lss_spin_0
.Lss_ok_0:
	v_pk_fma_f32 v[10:11], v[96:97], v[30:31], v[16:17] op_sel_hi:[1,0,1] neg_lo:[0,1,0] neg_hi:[0,1,0]
	v_pk_fma_f32 v[8:9], v[98:99], v[30:31], v[18:19] op_sel_hi:[1,0,1] neg_lo:[0,1,0] neg_hi:[0,1,0]
	v_pk_mul_f32 v[26:27], v[10:11], v[100:101] op_sel:[0,0] op_sel_hi:[0,1]
	v_pk_fma_f32 v[26:27], v[10:11], v[102:103], v[26:27] op_sel:[1,0,0] op_sel_hi:[1,1,1]
	v_pk_fma_f32 v[26:27], v[8:9], v[104:105], v[26:27] op_sel:[0,0,0] op_sel_hi:[0,1,1]
	v_pk_fma_f32 v[26:27], v[8:9], v[106:107], v[26:27] op_sel:[1,0,0] op_sel_hi:[1,1,1]
	s_waitcnt lgkmcnt(9)
	v_pk_fma_f32 v[16:17], v[108:109], v[162:163], v[10:11] op_sel_hi:[1,0,1]
	v_pk_fma_f32 v[18:19], v[110:111], v[162:163], v[8:9] op_sel_hi:[1,0,1]
	v_add_f32_dpp v15, v26, v26 row_ror:8 row_mask:0xf bank_mask:0xf bound_ctrl:1
	ds_read_b128 v[76:79], v48 offset:0
	s_nop 0
	v_add_f32_dpp v15, v15, v15 row_ror:4 row_mask:0xf bank_mask:0xf bound_ctrl:1
	ds_read_b128 v[80:83], v48 offset:256
	ds_read_b128 v[84:87], v48 offset:512
	v_add_f32_dpp v15, v15, v15 row_ror:2 row_mask:0xf bank_mask:0xf bound_ctrl:1
	ds_read_b128 v[88:91], v48 offset:768
	ds_read_b128 v[144:147], v48 offset:32768
	ds_write2st64_b32 v37, v25, v27 offset0:112 offset1:116
	v_add_f32_dpp v30, v15, v15 row_ror:1 row_mask:0xf bank_mask:0xf bound_ctrl:1
	ds_read_b128 v[156:159], v49 offset:0
	s_waitcnt lgkmcnt(7)
	v_pk_fma_f32 v[10:11], v[112:113], v[30:31], v[16:17] op_sel_hi:[1,0,1] neg_lo:[0,1,0] neg_hi:[0,1,0]
	v_pk_fma_f32 v[8:9], v[114:115], v[30:31], v[18:19] op_sel_hi:[1,0,1] neg_lo:[0,1,0] neg_hi:[0,1,0]
	v_pk_mul_f32 v[24:25], v[10:11], v[116:117] op_sel:[0,0] op_sel_hi:[0,1]
	v_pk_fma_f32 v[24:25], v[10:11], v[118:119], v[24:25] op_sel:[1,0,0] op_sel_hi:[1,1,1]
	v_pk_fma_f32 v[24:25], v[8:9], v[120:121], v[24:25] op_sel:[0,0,0] op_sel_hi:[0,1,1]
	v_pk_fma_f32 v[24:25], v[8:9], v[122:123], v[24:25] op_sel:[1,0,0] op_sel_hi:[1,1,1]
	v_pk_fma_f32 v[16:17], v[124:125], v[162:163], v[10:11] op_sel:[0,1,0] op_sel_hi:[1,1,1]
	v_pk_fma_f32 v[18:19], v[126:127], v[162:163], v[8:9] op_sel:[0,1,0] op_sel_hi:[1,1,1]
	v_add_f32_dpp v15, v24, v24 row_ror:8 row_mask:0xf bank_mask:0xf bound_ctrl:1
	ds_read_b128 v[92:95], v48 offset:1024
	s_nop 0
	v_add_f32_dpp v15, v15, v15 row_ror:4 row_mask:0xf bank_mask:0xf bound_ctrl:1
	ds_read_b128 v[96:99], v48 offset:1280
	ds_read_b128 v[100:103], v48 offset:1536
	v_add_f32_dpp v15, v15, v15 row_ror:2 row_mask:0xf bank_mask:0xf bound_ctrl:1
	ds_read_b128 v[104:107], v48 offset:1792
	s_nop 0
	v_add_f32_dpp v30, v15, v15 row_ror:1 row_mask:0xf bank_mask:0xf bound_ctrl:1
	v_pk_fma_f32 v[10:11], v[128:129], v[30:31], v[16:17] op_sel_hi:[1,0,1] neg_lo:[0,1,0] neg_hi:[0,1,0]
	v_pk_fma_f32 v[8:9], v[130:131], v[30:31], v[18:19] op_sel_hi:[1,0,1] neg_lo:[0,1,0] neg_hi:[0,1,0]
	v_pk_mul_f32 v[26:27], v[10:11], v[132:133] op_sel:[0,0] op_sel_hi:[0,1]
	v_pk_fma_f32 v[26:27], v[10:11], v[134:135], v[26:27] op_sel:[1,0,0] op_sel_hi:[1,1,1]
	v_pk_fma_f32 v[26:27], v[8:9], v[136:137], v[26:27] op_sel:[0,0,0] op_sel_hi:[0,1,1]
	v_pk_fma_f32 v[26:27], v[8:9], v[138:139], v[26:27] op_sel:[1,0,0] op_sel_hi:[1,1,1]
	ds_write2st64_b32 v37, v25, v27 offset0:120 offset1:124
	v_pk_mul_f32 v[10:11], v[10:11], v[140:141]
	v_pk_mul_f32 v[8:9], v[8:9], v[142:143]
	s_waitcnt lgkmcnt(7)
	v_pk_mul_f32 v[24:25], v[10:11], v[144:145]
	v_pk_fma_f32 v[24:25], v[8:9], v[146:147], v[24:25]
	v_add_f32_e32 v24, v24, v25
	s_waitcnt lgkmcnt(5)
	v_pk_fma_f32 v[16:17], v[76:77], v[156:157], v[10:11] op_sel_hi:[1,0,1]
	v_pk_fma_f32 v[18:19], v[78:79], v[156:157], v[8:9] op_sel_hi:[1,0,1]
	v_add_f32_dpp v15, v24, v24 row_ror:8 row_mask:0xf bank_mask:0xf bound_ctrl:1
	v_add_u32_e32 v51, 1, v51
	s_add_u32 s6, s6, 1
	v_add_f32_dpp v15, v15, v15 row_ror:4 row_mask:0xf bank_mask:0xf bound_ctrl:1
	ds_write_b32 v53, v51
	ds_read_b128 v[108:111], v48 offset:2048
	v_add_f32_dpp v15, v15, v15 row_ror:2 row_mask:0xf bank_mask:0xf bound_ctrl:1
	ds_read_b128 v[112:115], v48 offset:2304
	ds_read_b128 v[116:119], v48 offset:2560
	v_add_f32_dpp v30, v15, v15 row_ror:1 row_mask:0xf bank_mask:0xf bound_ctrl:1
	ds_read_b128 v[120:123], v48 offset:2816
	s_waitcnt lgkmcnt(4)
	v_pk_fma_f32 v[10:11], v[80:81], v[30:31], v[16:17] op_sel_hi:[1,0,1] neg_lo:[0,1,0] neg_hi:[0,1,0]
	v_pk_fma_f32 v[8:9], v[82:83], v[30:31], v[18:19] op_sel_hi:[1,0,1] neg_lo:[0,1,0] neg_hi:[0,1,0]
	v_pk_mul_f32 v[24:25], v[10:11], v[84:85] op_sel:[0,0] op_sel_hi:[0,1]
	v_pk_fma_f32 v[24:25], v[10:11], v[86:87], v[24:25] op_sel:[1,0,0] op_sel_hi:[1,1,1]
	v_pk_fma_f32 v[24:25], v[8:9], v[88:89], v[24:25] op_sel:[0,0,0] op_sel_hi:[0,1,1]
	v_pk_fma_f32 v[24:25], v[8:9], v[90:91], v[24:25] op_sel:[1,0,0] op_sel_hi:[1,1,1]
	v_pk_fma_f32 v[16:17], v[92:93], v[156:157], v[10:11] op_sel:[0,1,0] op_sel_hi:[1,1,1]
	v_pk_fma_f32 v[18:19], v[94:95], v[156:157], v[8:9] op_sel:[0,1,0] op_sel_hi:[1,1,1]
	v_add_f32_dpp v15, v24, v24 row_ror:8 row_mask:0xf bank_mask:0xf bound_ctrl:1
	ds_read_b128 v[124:127], v48 offset:3072
	s_nop 0
	v_add_f32_dpp v15, v15, v15 row_ror:4 row_mask:0xf bank_mask:0xf bound_ctrl:1
	ds_read_b128 v[128:131], v48 offset:3328
	ds_read_b128 v[132:135], v48 offset:3584
	v_add_f32_dpp v15, v15, v15 row_ror:2 row_mask:0xf bank_mask:0xf bound_ctrl:1
	ds_read_b128 v[136:139], v48 offset:3840
	ds_read_b128 v[160:163], v49 offset:16
	v_add_f32_dpp v30, v15, v15 row_ror:1 row_mask:0xf bank_mask:0xf bound_ctrl:1
	v_pk_fma_f32 v[10:11], v[96:97], v[30:31], v[16:17] op_sel_hi:[1,0,1] neg_lo:[0,1,0] neg_hi:[0,1,0]
	v_pk_fma_f32 v[8:9], v[98:99], v[30:31], v[18:19] op_sel_hi:[1,0,1] neg_lo:[0,1,0] neg_hi:[0,1,0]
	v_pk_mul_f32 v[26:27], v[10:11], v[100:101] op_sel:[0,0] op_sel_hi:[0,1]
	v_pk_fma_f32 v[26:27], v[10:11], v[102:103], v[26:27] op_sel:[1,0,0] op_sel_hi:[1,1,1]
	v_pk_fma_f32 v[26:27], v[8:9], v[104:105], v[26:27] op_sel:[0,0,0] op_sel_hi:[0,1,1]
	v_pk_fma_f32 v[26:27], v[8:9], v[106:107], v[26:27] op_sel:[1,0,0] op_sel_hi:[1,1,1]
	s_waitcnt lgkmcnt(8)
	v_pk_fma_f32 v[16:17], v[108:109], v[158:159], v[10:11] op_sel_hi:[1,0,1]
	v_pk_fma_f32 v[18:19], v[110:111], v[158:159], v[8:9] op_sel_hi:[1,0,1]
	v_add_f32_dpp v15, v26, v26 row_ror:8 row_mask:0xf bank_mask:0xf bound_ctrl:1
	ds_read_b128 v[76:79], v48 offset:4096
	s_nop 0
	v_add_f32_dpp v15, v15, v15 row_ror:4 row_mask:0xf bank_mask:0xf bound_ctrl:1
	ds_read_b128 v[80:83], v48 offset:4352
	ds_read_b128 v[84:87], v48 offset:4608
	v_add_f32_dpp v15, v15, v15 row_ror:2 row_mask:0xf bank_mask:0xf bound_ctrl:1
	ds_read_b128 v[88:91], v48 offset:4864
	ds_write2st64_b32 v50, v25, v27 offset0:0 offset1:4
	v_add_f32_dpp v30, v15, v15 row_ror:1 row_mask:0xf bank_mask:0xf bound_ctrl:1
	s_waitcnt lgkmcnt(5)
	v_pk_fma_f32 v[10:11], v[112:113], v[30:31], v[16:17] op_sel_hi:[1,0,1] neg_lo:[0,1,0] neg_hi:[0,1,0]
	v_pk_fma_f32 v[8:9], v[114:115], v[30:31], v[18:19] op_sel_hi:[1,0,1] neg_lo:[0,1,0] neg_hi:[0,1,0]
	v_pk_mul_f32 v[24:25], v[10:11], v[116:117] op_sel:[0,0] op_sel_hi:[0,1]
	v_pk_fma_f32 v[24:25], v[10:11], v[118:119], v[24:25] op_sel:[1,0,0] op_sel_hi:[1,1,1]
	v_pk_fma_f32 v[24:25], v[8:9], v[120:121], v[24:25] op_sel:[0,0,0] op_sel_hi:[0,1,1]
	v_pk_fma_f32 v[24:25], v[8:9], v[122:123], v[24:25] op_sel:[1,0,0] op_sel_hi:[1,1,1]
	v_pk_fma_f32 v[16:17], v[124:125], v[158:159], v[10:11] op_sel:[0,1,0] op_sel_hi:[1,1,1]
	v_pk_fma_f32 v[18:19], v[126:127], v[158:159], v[8:9] op_sel:[0,1,0] op_sel_hi:[1,1,1]
	v_add_f32_dpp v15, v24, v24 row_ror:8 row_mask:0xf bank_mask:0xf bound_ctrl:1
	ds_read_b128 v[92:95], v48 offset:5120
	s_nop 0
	v_add_f32_dpp v15, v15, v15 row_ror:4 row_mask:0xf bank_mask:0xf bound_ctrl:1
	ds_read_b128 v[96:99], v48 offset:5376
	ds_read_b128 v[100:103], v48 offset:5632
	v_add_f32_dpp v15, v15, v15 row_ror:2 row_mask:0xf bank_mask:0xf bound_ctrl:1
	ds_read_b128 v[104:107], v48 offset:5888
	s_nop 0
	v_add_f32_dpp v30, v15, v15 row_ror:1 row_mask:0xf bank_mask:0xf bound_ctrl:1
	v_pk_fma_f32 v[10:11], v[128:129], v[30:31], v[16:17] op_sel_hi:[1,0,1] neg_lo:[0,1,0] neg_hi:[0,1,0]
	v_pk_fma_f32 v[8:9], v[130:131], v[30:31], v[18:19] op_sel_hi:[1,0,1] neg_lo:[0,1,0] neg_hi:[0,1,0]
	v_pk_mul_f32 v[26:27], v[10:11], v[132:133] op_sel:[0,0] op_sel_hi:[0,1]
	v_pk_fma_f32 v[26:27], v[10:11], v[134:135], v[26:27] op_sel:[1,0,0] op_sel_hi:[1,1,1]
	v_pk_fma_f32 v[26:27], v[8:9], v[136:137], v[26:27] op_sel:[0,0,0] op_sel_hi:[0,1,1]
	v_pk_fma_f32 v[26:27], v[8:9], v[138:139], v[26:27] op_sel:[1,0,0] op_sel_hi:[1,1,1]
	s_waitcnt lgkmcnt(8)
	v_pk_fma_f32 v[16:17], v[76:77], v[160:161], v[10:11] op_sel_hi:[1,0,1]
	v_pk_fma_f32 v[18:19], v[78:79], v[160:161], v[8:9] op_sel_hi:[1,0,1]
	v_add_f32_dpp v15, v26, v26 row_ror:8 row_mask:0xf bank_mask:0xf bound_ctrl:1
	ds_read_b128 v[108:111], v48 offset:6144
	s_nop 0
	v_add_f32_dpp v15, v15, v15 row_ror:4 row_mask:0xf bank_mask:0xf bound_ctrl:1
	ds_read_b128 v[112:115], v48 offset:6400
	ds_read_b128 v[116:119], v48 offset:6656
	v_add_f32_dpp v15, v15, v15 row_ror:2 row_mask:0xf bank_mask:0xf bound_ctrl:1
	ds_read_b128 v[120:123], v48 offset:6912
	ds_write2st64_b32 v50, v25, v27 offset0:8 offset1:12
	v_add_f32_dpp v30, v15, v15 row_ror:1 row_mask:0xf bank_mask:0xf bound_ctrl:1
	s_waitcnt lgkmcnt(5)
	v_pk_fma_f32 v[10:11], v[80:81], v[30:31], v[16:17] op_sel_hi:[1,0,1] neg_lo:[0,1,0] neg_hi:[0,1,0]
	v_pk_fma_f32 v[8:9], v[82:83], v[30:31], v[18:19] op_sel_hi:[1,0,1] neg_lo:[0,1,0] neg_hi:[0,1,0]
	v_pk_mul_f32 v[24:25], v[10:11], v[84:85] op_sel:[0,0] op_sel_hi:[0,1]
	v_pk_fma_f32 v[24:25], v[10:11], v[86:87], v[24:25] op_sel:[1,0,0] op_sel_hi:[1,1,1]
	v_pk_fma_f32 v[24:25], v[8:9], v[88:89], v[24:25] op_sel:[0,0,0] op_sel_hi:[0,1,1]
	v_pk_fma_f32 v[24:25], v[8:9], v[90:91], v[24:25] op_sel:[1,0,0] op_sel_hi:[1,1,1]
	v_pk_fma_f32 v[16:17], v[92:93], v[160:161], v[10:11] op_sel:[0,1,0] op_sel_hi:[1,1,1]
	v_pk_fma_f32 v[18:19], v[94:95], v[160:161], v[8:9] op_sel:[0,1,0] op_sel_hi:[1,1,1]
	v_add_f32_dpp v15, v24, v24 row_ror:8 row_mask:0xf bank_mask:0xf bound_ctrl:1
	ds_read_b128 v[124:127], v48 offset:7168
	s_nop 0
	v_add_f32_dpp v15, v15, v15 row_ror:4 row_mask:0xf bank_mask:0xf bound_ctrl:1
	ds_read_b128 v[128:131], v48 offset:7424
	ds_read_b128 v[132:135], v48 offset:7680
	v_add_f32_dpp v15, v15, v15 row_ror:2 row_mask:0xf bank_mask:0xf bound_ctrl:1
	ds_read_b128 v[136:139], v48 offset:7936
	ds_read_b128 v[156:159], v49 offset:32
	v_add_f32_dpp v30, v15, v15 row_ror:1 row_mask:0xf bank_mask:0xf bound_ctrl:1
	v_pk_fma_f32 v[10:11], v[96:97], v[30:31], v[16:17] op_sel_hi:[1,0,1] neg_lo:[0,1,0] neg_hi:[0,1,0]
	v_pk_fma_f32 v[8:9], v[98:99], v[30:31], v[18:19] op_sel_hi:[1,0,1] neg_lo:[0,1,0] neg_hi:[0,1,0]
	v_pk_mul_f32 v[26:27], v[10:11], v[100:101] op_sel:[0,0] op_sel_hi:[0,1]
	v_pk_fma_f32 v[26:27], v[10:11], v[102:103], v[26:27] op_sel:[1,0,0] op_sel_hi:[1,1,1]
	v_pk_fma_f32 v[26:27], v[8:9], v[104:105], v[26:27] op_sel:[0,0,0] op_sel_hi:[0,1,1]
	v_pk_fma_f32 v[26:27], v[8:9], v[106:107], v[26:27] op_sel:[1,0,0] op_sel_hi:[1,1,1]
	s_waitcnt lgkmcnt(9)
	v_pk_fma_f32 v[16:17], v[108:109], v[162:163], v[10:11] op_sel_hi:[1,0,1]
	v_pk_fma_f32 v[18:19], v[110:111], v[162:163], v[8:9] op_sel_hi:[1,0,1]
	v_add_f32_dpp v15, v26, v26 row_ror:8 row_mask:0xf bank_mask:0xf bound_ctrl:1
	ds_read_b128 v[76:79], v48 offset:8192
	s_nop 0
	v_add_f32_dpp v15, v15, v15 row_ror:4 row_mask:0xf bank_mask:0xf bound_ctrl:1
	ds_read_b128 v[80:83], v48 offset:8448
	ds_read_b128 v[84:87], v48 offset:8704
	v_add_f32_dpp v15, v15, v15 row_ror:2 row_mask:0xf bank_mask:0xf bound_ctrl:1
	ds_read_b128 v[88:91], v48 offset:8960
	ds_write2st64_b32 v50, v25, v27 offset0:16 offset1:20
	v_add_f32_dpp v30, v15, v15 row_ror:1 row_mask:0xf bank_mask:0xf bound_ctrl:1
	s_waitcnt lgkmcnt(5)
	v_pk_fma_f32 v[10:11], v[112:113], v[30:31], v[16:17] op_sel_hi:[1,0,1] neg_lo:[0,1,0] neg_hi:[0,1,0]
	v_pk_fma_f32 v[8:9], v[114:115], v[30:31], v[18:19] op_sel_hi:[1,0,1] neg_lo:[0,1,0] neg_hi:[0,1,0]
	v_pk_mul_f32 v[24:25], v[10:11], v[116:117] op_sel:[0,0] op_sel_hi:[0,1]
	v_pk_fma_f32 v[24:25], v[10:11], v[118:119], v[24:25] op_sel:[1,0,0] op_sel_hi:[1,1,1]
	v_pk_fma_f32 v[24:25], v[8:9], v[120:121], v[24:25] op_sel:[0,0,0] op_sel_hi:[0,1,1]
	v_pk_fma_f32 v[24:25], v[8:9], v[122:123], v[24:25] op_sel:[1,0,0] op_sel_hi:[1,1,1]
	v_pk_fma_f32 v[16:17], v[124:125], v[162:163], v[10:11] op_sel:[0,1,0] op_sel_hi:[1,1,1]
	v_pk_fma_f32 v[18:19], v[126:127], v[162:163], v[8:9] op_sel:[0,1,0] op_sel_hi:[1,1,1]
	v_add_f32_dpp v15, v24, v24 row_ror:8 row_mask:0xf bank_mask:0xf bound_ctrl:1
	ds_read_b128 v[92:95], v48 offset:9216
	s_nop 0
	v_add_f32_dpp v15, v15, v15 row_ror:4 row_mask:0xf bank_mask:0xf bound_ctrl:1
	ds_read_b128 v[96:99], v48 offset:9472
	ds_read_b128 v[100:103], v48 offset:9728
	v_add_f32_dpp v15, v15, v15 row_ror:2 row_mask:0xf bank_mask:0xf bound_ctrl:1
	ds_read_b128 v[104:107], v48 offset:9984
	s_nop 0
	v_add_f32_dpp v30, v15, v15 row_ror:1 row_mask:0xf bank_mask:0xf bound_ctrl:1
	v_pk_fma_f32 v[10:11], v[128:129], v[30:31], v[16:17] op_sel_hi:[1,0,1] neg_lo:[0,1,0] neg_hi:[0,1,0]
	v_pk_fma_f32 v[8:9], v[130:131], v[30:31], v[18:19] op_sel_hi:[1,0,1] neg_lo:[0,1,0] neg_hi:[0,1,0]
	v_pk_mul_f32 v[26:27], v[10:11], v[132:133] op_sel:[0,0] op_sel_hi:[0,1]
	v_pk_fma_f32 v[26:27], v[10:11], v[134:135], v[26:27] op_sel:[1,0,0] op_sel_hi:[1,1,1]
	v_pk_fma_f32 v[26:27], v[8:9], v[136:137], v[26:27] op_sel:[0,0,0] op_sel_hi:[0,1,1]
	v_pk_fma_f32 v[26:27], v[8:9], v[138:139], v[26:27] op_sel:[1,0,0] op_sel_hi:[1,1,1]
	s_waitcnt lgkmcnt(8)
	v_pk_fma_f32 v[16:17], v[76:77], v[156:157], v[10:11] op_sel_hi:[1,0,1]
	v_pk_fma_f32 v[18:19], v[78:79], v[156:157], v[8:9] op_sel_hi:[1,0,1]
	v_add_f32_dpp v15, v26, v26 row_ror:8 row_mask:0xf bank_mask:0xf bound_ctrl:1
	ds_read_b128 v[108:111], v48 offset:10240
	s_nop 0
	v_add_f32_dpp v15, v15, v15 row_ror:4 row_mask:0xf bank_mask:0xf bound_ctrl:1
	ds_read_b128 v[112:115], v48 offset:10496
	ds_read_b128 v[116:119], v48 offset:10752
	v_add_f32_dpp v15, v15, v15 row_ror:2 row_mask:0xf bank_mask:0xf bound_ctrl:1
	ds_read_b128 v[120:123], v48 offset:11008
	ds_write2st64_b32 v50, v25, v27 offset0:24 offset1:28
	v_add_f32_dpp v30, v15, v15 row_ror:1 row_mask:0xf bank_mask:0xf bound_ctrl:1
	s_waitcnt lgkmcnt(5)
	v_pk_fma_f32 v[10:11], v[80:81], v[30:31], v[16:17] op_sel_hi:[1,0,1] neg_lo:[0,1,0] neg_hi:[0,1,0]
	v_pk_fma_f32 v[8:9], v[82:83], v[30:31], v[18:19] op_sel_hi:[1,0,1] neg_lo:[0,1,0] neg_hi:[0,1,0]
	v_pk_mul_f32 v[24:25], v[10:11], v[84:85] op_sel:[0,0] op_sel_hi:[0,1]
	v_pk_fma_f32 v[24:25], v[10:11], v[86:87], v[24:25] op_sel:[1,0,0] op_sel_hi:[1,1,1]
	v_pk_fma_f32 v[24:25], v[8:9], v[88:89], v[24:25] op_sel:[0,0,0] op_sel_hi:[0,1,1]
	v_pk_fma_f32 v[24:25], v[8:9], v[90:91], v[24:25] op_sel:[1,0,0] op_sel_hi:[1,1,1]
	v_pk_fma_f32 v[16:17], v[92:93], v[156:157], v[10:11] op_sel:[0,1,0] op_sel_hi:[1,1,1]
	v_pk_fma_f32 v[18:19], v[94:95], v[156:157], v[8:9] op_sel:[0,1,0] op_sel_hi:[1,1,1]
	v_add_f32_dpp v15, v24, v24 row_ror:8 row_mask:0xf bank_mask:0xf bound_ctrl:1
	ds_read_b128 v[124:127], v48 offset:11264
	s_nop 0
	v_add_f32_dpp v15, v15, v15 row_ror:4 row_mask:0xf bank_mask:0xf bound_ctrl:1
	ds_read_b128 v[128:131], v48 offset:11520
	ds_read_b128 v[132:135], v48 offset:11776
	v_add_f32_dpp v15, v15, v15 row_ror:2 row_mask:0xf bank_mask:0xf bound_ctrl:1
	ds_read_b128 v[136:139], v48 offset:12032
	ds_read_b128 v[160:163], v49 offset:48
	v_add_f32_dpp v30, v15, v15 row_ror:1 row_mask:0xf bank_mask:0xf bound_ctrl:1
	v_pk_fma_f32 v[10:11], v[96:97], v[30:31], v[16:17] op_sel_hi:[1,0,1] neg_lo:[0,1,0] neg_hi:[0,1,0]
	v_pk_fma_f32 v[8:9], v[98:99], v[30:31], v[18:19] op_sel_hi:[1,0,1] neg_lo:[0,1,0] neg_hi:[0,1,0]
	v_pk_mul_f32 v[26:27], v[10:11], v[100:101] op_sel:[0,0] op_sel_hi:[0,1]
	v_pk_fma_f32 v[26:27], v[10:11], v[102:103], v[26:27] op_sel:[1,0,0] op_sel_hi:[1,1,1]
	v_pk_fma_f32 v[26:27], v[8:9], v[104:105], v[26:27] op_sel:[0,0,0] op_sel_hi:[0,1,1]
	v_pk_fma_f32 v[26:27], v[8:9], v[106:107], v[26:27] op_sel:[1,0,0] op_sel_hi:[1,1,1]
	s_waitcnt lgkmcnt(9)
	v_pk_fma_f32 v[16:17], v[108:109], v[158:159], v[10:11] op_sel_hi:[1,0,1]
	v_pk_fma_f32 v[18:19], v[110:111], v[158:159], v[8:9] op_sel_hi:[1,0,1]
	v_add_f32_dpp v15, v26, v26 row_ror:8 row_mask:0xf bank_mask:0xf bound_ctrl:1
	ds_read_b128 v[76:79], v48 offset:12288
	s_nop 0
	v_add_f32_dpp v15, v15, v15 row_ror:4 row_mask:0xf bank_mask:0xf bound_ctrl:1
	ds_read_b128 v[80:83], v48 offset:12544
	ds_read_b128 v[84:87], v48 offset:12800
	v_add_f32_dpp v15, v15, v15 row_ror:2 row_mask:0xf bank_mask:0xf bound_ctrl:1
	ds_read_b128 v[88:91], v48 offset:13056
	ds_write2st64_b32 v50, v25, v27 offset0:32 offset1:36
	v_add_f32_dpp v30, v15, v15 row_ror:1 row_mask:0xf bank_mask:0xf bound_ctrl:1
	s_waitcnt lgkmcnt(5)
	v_pk_fma_f32 v[10:11], v[112:113], v[30:31], v[16:17] op_sel_hi:[1,0,1] neg_lo:[0,1,0] neg_hi:[0,1,0]
	v_pk_fma_f32 v[8:9], v[114:115], v[30:31], v[18:19] op_sel_hi:[1,0,1] neg_lo:[0,1,0] neg_hi:[0,1,0]
	v_pk_mul_f32 v[24:25], v[10:11], v[116:117] op_sel:[0,0] op_sel_hi:[0,1]
	v_pk_fma_f32 v[24:25], v[10:11], v[118:119], v[24:25] op_sel:[1,0,0] op_sel_hi:[1,1,1]
	v_pk_fma_f32 v[24:25], v[8:9], v[120:121], v[24:25] op_sel:[0,0,0] op_sel_hi:[0,1,1]
	v_pk_fma_f32 v[24:25], v[8:9], v[122:123], v[24:25] op_sel:[1,0,0] op_sel_hi:[1,1,1]
	v_pk_fma_f32 v[16:17], v[124:125], v[158:159], v[10:11] op_sel:[0,1,0] op_sel_hi:[1,1,1]
	v_pk_fma_f32 v[18:19], v[126:127], v[158:159], v[8:9] op_sel:[0,1,0] op_sel_hi:[1,1,1]
	v_add_f32_dpp v15, v24, v24 row_ror:8 row_mask:0xf bank_mask:0xf bound_ctrl:1
	ds_read_b128 v[92:95], v48 offset:13312
	s_nop 0
	v_add_f32_dpp v15, v15, v15 row_ror:4 row_mask:0xf bank_mask:0xf bound_ctrl:1
	ds_read_b128 v[96:99], v48 offset:13568
	ds_read_b128 v[100:103], v48 offset:13824
	v_add_f32_dpp v15, v15, v15 row_ror:2 row_mask:0xf bank_mask:0xf bound_ctrl:1
	ds_read_b128 v[104:107], v48 offset:14080
	s_nop 0
	v_add_f32_dpp v30, v15, v15 row_ror:1 row_mask:0xf bank_mask:0xf bound_ctrl:1
	v_pk_fma_f32 v[10:11], v[128:129], v[30:31], v[16:17] op_sel_hi:[1,0,1] neg_lo:[0,1,0] neg_hi:[0,1,0]
	v_pk_fma_f32 v[8:9], v[130:131], v[30:31], v[18:19] op_sel_hi:[1,0,1] neg_lo:[0,1,0] neg_hi:[0,1,0]
	v_pk_mul_f32 v[26:27], v[10:11], v[132:133] op_sel:[0,0] op_sel_hi:[0,1]
	v_pk_fma_f32 v[26:27], v[10:11], v[134:135], v[26:27] op_sel:[1,0,0] op_sel_hi:[1,1,1]
	v_pk_fma_f32 v[26:27], v[8:9], v[136:137], v[26:27] op_sel:[0,0,0] op_sel_hi:[0,1,1]
	v_pk_fma_f32 v[26:27], v[8:9], v[138:139], v[26:27] op_sel:[1,0,0] op_sel_hi:[1,1,1]
	s_waitcnt lgkmcnt(8)
	v_pk_fma_f32 v[16:17], v[76:77], v[160:161], v[10:11] op_sel_hi:[1,0,1]
	v_pk_fma_f32 v[18:19], v[78:79], v[160:161], v[8:9] op_sel_hi:[1,0,1]
	v_add_f32_dpp v15, v26, v26 row_ror:8 row_mask:0xf bank_mask:0xf bound_ctrl:1
	ds_read_b128 v[108:111], v48 offset:14336
	s_nop 0
	v_add_f32_dpp v15, v15, v15 row_ror:4 row_mask:0xf bank_mask:0xf bound_ctrl:1
	ds_read_b128 v[112:115], v48 offset:14592
	ds_read_b128 v[116:119], v48 offset:14848
	v_add_f32_dpp v15, v15, v15 row_ror:2 row_mask:0xf bank_mask:0xf bound_ctrl:1
	ds_read_b128 v[120:123], v48 offset:15104
	ds_write2st64_b32 v50, v25, v27 offset0:40 offset1:44
	v_add_f32_dpp v30, v15, v15 row_ror:1 row_mask:0xf bank_mask:0xf bound_ctrl:1
	s_waitcnt lgkmcnt(5)
	v_pk_fma_f32 v[10:11], v[80:81], v[30:31], v[16:17] op_sel_hi:[1,0,1] neg_lo:[0,1,0] neg_hi:[0,1,0]
	v_pk_fma_f32 v[8:9], v[82:83], v[30:31], v[18:19] op_sel_hi:[1,0,1] neg_lo:[0,1,0] neg_hi:[0,1,0]
	v_pk_mul_f32 v[24:25], v[10:11], v[84:85] op_sel:[0,0] op_sel_hi:[0,1]
	v_pk_fma_f32 v[24:25], v[10:11], v[86:87], v[24:25] op_sel:[1,0,0] op_sel_hi:[1,1,1]
	v_pk_fma_f32 v[24:25], v[8:9], v[88:89], v[24:25] op_sel:[0,0,0] op_sel_hi:[0,1,1]
	v_pk_fma_f32 v[24:25], v[8:9], v[90:91], v[24:25] op_sel:[1,0,0] op_sel_hi:[1,1,1]
	v_pk_fma_f32 v[16:17], v[92:93], v[160:161], v[10:11] op_sel:[0,1,0] op_sel_hi:[1,1,1]
	v_pk_fma_f32 v[18:19], v[94:95], v[160:161], v[8:9] op_sel:[0,1,0] op_sel_hi:[1,1,1]
	v_add_f32_dpp v15, v24, v24 row_ror:8 row_mask:0xf bank_mask:0xf bound_ctrl:1
	ds_read_b128 v[124:127], v48 offset:15360
	s_nop 0
	v_add_f32_dpp v15, v15, v15 row_ror:4 row_mask:0xf bank_mask:0xf bound_ctrl:1
	ds_read_b128 v[128:131], v48 offset:15616
	ds_read_b128 v[132:135], v48 offset:15872
	v_add_f32_dpp v15, v15, v15 row_ror:2 row_mask:0xf bank_mask:0xf bound_ctrl:1
	ds_read_b128 v[136:139], v48 offset:16128
	ds_read_b128 v[156:159], v49 offset:64
	v_add_f32_dpp v30, v15, v15 row_ror:1 row_mask:0xf bank_mask:0xf bound_ctrl:1
	v_pk_fma_f32 v[10:11], v[96:97], v[30:31], v[16:17] op_sel_hi:[1,0,1] neg_lo:[0,1,0] neg_hi:[0,1,0]
	v_pk_fma_f32 v[8:9], v[98:99], v[30:31], v[18:19] op_sel_hi:[1,0,1] neg_lo:[0,1,0] neg_hi:[0,1,0]
	v_pk_mul_f32 v[26:27], v[10:11], v[100:101] op_sel:[0,0] op_sel_hi:[0,1]
	v_pk_fma_f32 v[26:27], v[10:11], v[102:103], v[26:27] op_sel:[1,0,0] op_sel_hi:[1,1,1]
	v_pk_fma_f32 v[26:27], v[8:9], v[104:105], v[26:27] op_sel:[0,0,0] op_sel_hi:[0,1,1]
	v_pk_fma_f32 v[26:27], v[8:9], v[106:107], v[26:27] op_sel:[1,0,0] op_sel_hi:[1,1,1]
	s_waitcnt lgkmcnt(9)
	v_pk_fma_f32 v[16:17], v[108:109], v[162:163], v[10:11] op_sel_hi:[1,0,1]
	v_pk_fma_f32 v[18:19], v[110:111], v[162:163], v[8:9] op_sel_hi:[1,0,1]
	v_add_f32_dpp v15, v26, v26 row_ror:8 row_mask:0xf bank_mask:0xf bound_ctrl:1
	ds_read_b128 v[76:79], v48 offset:16384
	s_nop 0
	v_add_f32_dpp v15, v15, v15 row_ror:4 row_mask:0xf bank_mask:0xf bound_ctrl:1
	ds_read_b128 v[80:83], v48 offset:16640
	ds_read_b128 v[84:87], v48 offset:16896
	v_add_f32_dpp v15, v15, v15 row_ror:2 row_mask:0xf bank_mask:0xf bound_ctrl:1
	ds_read_b128 v[88:91], v48 offset:17152
	ds_write2st64_b32 v50, v25, v27 offset0:48 offset1:52
	v_add_f32_dpp v30, v15, v15 row_ror:1 row_mask:0xf bank_mask:0xf bound_ctrl:1
	s_waitcnt lgkmcnt(5)
	v_pk_fma_f32 v[10:11], v[112:113], v[30:31], v[16:17] op_sel_hi:[1,0,1] neg_lo:[0,1,0] neg_hi:[0,1,0]
	v_pk_fma_f32 v[8:9], v[114:115], v[30:31], v[18:19] op_sel_hi:[1,0,1] neg_lo:[0,1,0] neg_hi:[0,1,0]
	v_pk_mul_f32 v[24:25], v[10:11], v[116:117] op_sel:[0,0] op_sel_hi:[0,1]
	v_pk_fma_f32 v[24:25], v[10:11], v[118:119], v[24:25] op_sel:[1,0,0] op_sel_hi:[1,1,1]
	v_pk_fma_f32 v[24:25], v[8:9], v[120:121], v[24:25] op_sel:[0,0,0] op_sel_hi:[0,1,1]
	v_pk_fma_f32 v[24:25], v[8:9], v[122:123], v[24:25] op_sel:[1,0,0] op_sel_hi:[1,1,1]
	v_pk_fma_f32 v[16:17], v[124:125], v[162:163], v[10:11] op_sel:[0,1,0] op_sel_hi:[1,1,1]
	v_pk_fma_f32 v[18:19], v[126:127], v[162:163], v[8:9] op_sel:[0,1,0] op_sel_hi:[1,1,1]
	v_add_f32_dpp v15, v24, v24 row_ror:8 row_mask:0xf bank_mask:0xf bound_ctrl:1
	ds_read_b128 v[92:95], v48 offset:17408
	s_nop 0
	v_add_f32_dpp v15, v15, v15 row_ror:4 row_mask:0xf bank_mask:0xf bound_ctrl:1
	ds_read_b128 v[96:99], v48 offset:17664
	ds_read_b128 v[100:103], v48 offset:17920
	v_add_f32_dpp v15, v15, v15 row_ror:2 row_mask:0xf bank_mask:0xf bound_ctrl:1
	ds_read_b128 v[104:107], v48 offset:18176
	s_nop 0
	v_add_f32_dpp v30, v15, v15 row_ror:1 row_mask:0xf bank_mask:0xf bound_ctrl:1
	v_pk_fma_f32 v[10:11], v[128:129], v[30:31], v[16:17] op_sel_hi:[1,0,1] neg_lo:[0,1,0] neg_hi:[0,1,0]
	v_pk_fma_f32 v[8:9], v[130:131], v[30:31], v[18:19] op_sel_hi:[1,0,1] neg_lo:[0,1,0] neg_hi:[0,1,0]
	v_pk_mul_f32 v[26:27], v[10:11], v[132:133] op_sel:[0,0] op_sel_hi:[0,1]
	v_pk_fma_f32 v[26:27], v[10:11], v[134:135], v[26:27] op_sel:[1,0,0] op_sel_hi:[1,1,1]
	v_pk_fma_f32 v[26:27], v[8:9], v[136:137], v[26:27] op_sel:[0,0,0] op_sel_hi:[0,1,1]
	v_pk_fma_f32 v[26:27], v[8:9], v[138:139], v[26:27] op_sel:[1,0,0] op_sel_hi:[1,1,1]
	s_waitcnt lgkmcnt(8)
	v_pk_fma_f32 v[16:17], v[76:77], v[156:157], v[10:11] op_sel_hi:[1,0,1]
	v_pk_fma_f32 v[18:19], v[78:79], v[156:157], v[8:9] op_sel_hi:[1,0,1]
	v_add_f32_dpp v15, v26, v26 row_ror:8 row_mask:0xf bank_mask:0xf bound_ctrl:1
	ds_read_b128 v[108:111], v48 offset:18432
	s_nop 0
	v_add_f32_dpp v15, v15, v15 row_ror:4 row_mask:0xf bank_mask:0xf bound_ctrl:1
	ds_read_b128 v[112:115], v48 offset:18688
	ds_read_b128 v[116:119], v48 offset:18944
	v_add_f32_dpp v15, v15, v15 row_ror:2 row_mask:0xf bank_mask:0xf bound_ctrl:1
	ds_read_b128 v[120:123], v48 offset:19200
	ds_write2st64_b32 v50, v25, v27 offset0:56 offset1:60
	v_add_f32_dpp v30, v15, v15 row_ror:1 row_mask:0xf bank_mask:0xf bound_ctrl:1
	s_waitcnt lgkmcnt(5)
	v_pk_fma_f32 v[10:11], v[80:81], v[30:31], v[16:17] op_sel_hi:[1,0,1] neg_lo:[0,1,0] neg_hi:[0,1,0]
	v_pk_fma_f32 v[8:9], v[82:83], v[30:31], v[18:19] op_sel_hi:[1,0,1] neg_lo:[0,1,0] neg_hi:[0,1,0]
	v_pk_mul_f32 v[24:25], v[10:11], v[84:85] op_sel:[0,0] op_sel_hi:[0,1]
	v_pk_fma_f32 v[24:25], v[10:11], v[86:87], v[24:25] op_sel:[1,0,0] op_sel_hi:[1,1,1]
	v_pk_fma_f32 v[24:25], v[8:9], v[88:89], v[24:25] op_sel:[0,0,0] op_sel_hi:[0,1,1]
	v_pk_fma_f32 v[24:25], v[8:9], v[90:91], v[24:25] op_sel:[1,0,0] op_sel_hi:[1,1,1]
	v_pk_fma_f32 v[16:17], v[92:93], v[156:157], v[10:11] op_sel:[0,1,0] op_sel_hi:[1,1,1]
	v_pk_fma_f32 v[18:19], v[94:95], v[156:157], v[8:9] op_sel:[0,1,0] op_sel_hi:[1,1,1]
	v_add_f32_dpp v15, v24, v24 row_ror:8 row_mask:0xf bank_mask:0xf bound_ctrl:1
	ds_read_b128 v[124:127], v48 offset:19456
	s_nop 0
	v_add_f32_dpp v15, v15, v15 row_ror:4 row_mask:0xf bank_mask:0xf bound_ctrl:1
	ds_read_b128 v[128:131], v48 offset:19712
	ds_read_b128 v[132:135], v48 offset:19968
	v_add_f32_dpp v15, v15, v15 row_ror:2 row_mask:0xf bank_mask:0xf bound_ctrl:1
	ds_read_b128 v[136:139], v48 offset:20224
	ds_read_b128 v[160:163], v49 offset:80
	v_add_f32_dpp v30, v15, v15 row_ror:1 row_mask:0xf bank_mask:0xf bound_ctrl:1
	v_pk_fma_f32 v[10:11], v[96:97], v[30:31], v[16:17] op_sel_hi:[1,0,1] neg_lo:[0,1,0] neg_hi:[0,1,0]
	v_pk_fma_f32 v[8:9], v[98:99], v[30:31], v[18:19] op_sel_hi:[1,0,1] neg_lo:[0,1,0] neg_hi:[0,1,0]
	v_pk_mul_f32 v[26:27], v[10:11], v[100:101] op_sel:[0,0] op_sel_hi:[0,1]
	v_pk_fma_f32 v[26:27], v[10:11], v[102:103], v[26:27] op_sel:[1,0,0] op_sel_hi:[1,1,1]
	v_pk_fma_f32 v[26:27], v[8:9], v[104:105], v[26:27] op_sel:[0,0,0] op_sel_hi:[0,1,1]
	v_pk_fma_f32 v[26:27], v[8:9], v[106:107], v[26:27] op_sel:[1,0,0] op_sel_hi:[1,1,1]
	s_waitcnt lgkmcnt(9)
	v_pk_fma_f32 v[16:17], v[108:109], v[158:159], v[10:11] op_sel_hi:[1,0,1]
	v_pk_fma_f32 v[18:19], v[110:111], v[158:159], v[8:9] op_sel_hi:[1,0,1]
	v_add_f32_dpp v15, v26, v26 row_ror:8 row_mask:0xf bank_mask:0xf bound_ctrl:1
	ds_read_b128 v[76:79], v48 offset:20480
	s_nop 0
	v_add_f32_dpp v15, v15, v15 row_ror:4 row_mask:0xf bank_mask:0xf bound_ctrl:1
	ds_read_b128 v[80:83], v48 offset:20736
	ds_read_b128 v[84:87], v48 offset:20992
	v_add_f32_dpp v15, v15, v15 row_ror:2 row_mask:0xf bank_mask:0xf bound_ctrl:1
	ds_read_b128 v[88:91], v48 offset:21248
	ds_write2st64_b32 v50, v25, v27 offset0:64 offset1:68
	v_add_f32_dpp v30, v15, v15 row_ror:1 row_mask:0xf bank_mask:0xf bound_ctrl:1
	s_waitcnt lgkmcnt(5)
	v_pk_fma_f32 v[10:11], v[112:113], v[30:31], v[16:17] op_sel_hi:[1,0,1] neg_lo:[0,1,0] neg_hi:[0,1,0]
	v_pk_fma_f32 v[8:9], v[114:115], v[30:31], v[18:19] op_sel_hi:[1,0,1] neg_lo:[0,1,0] neg_hi:[0,1,0]
	v_pk_mul_f32 v[24:25], v[10:11], v[116:117] op_sel:[0,0] op_sel_hi:[0,1]
	v_pk_fma_f32 v[24:25], v[10:11], v[118:119], v[24:25] op_sel:[1,0,0] op_sel_hi:[1,1,1]
	v_pk_fma_f32 v[24:25], v[8:9], v[120:121], v[24:25] op_sel:[0,0,0] op_sel_hi:[0,1,1]
	v_pk_fma_f32 v[24:25], v[8:9], v[122:123], v[24:25] op_sel:[1,0,0] op_sel_hi:[1,1,1]
	v_pk_fma_f32 v[16:17], v[124:125], v[158:159], v[10:11] op_sel:[0,1,0] op_sel_hi:[1,1,1]
	v_pk_fma_f32 v[18:19], v[126:127], v[158:159], v[8:9] op_sel:[0,1,0] op_sel_hi:[1,1,1]
	v_add_f32_dpp v15, v24, v24 row_ror:8 row_mask:0xf bank_mask:0xf bound_ctrl:1
	ds_read_b128 v[92:95], v48 offset:21504
	s_nop 0
	v_add_f32_dpp v15, v15, v15 row_ror:4 row_mask:0xf bank_mask:0xf bound_ctrl:1
	ds_read_b128 v[96:99], v48 offset:21760
	ds_read_b128 v[100:103], v48 offset:22016
	v_add_f32_dpp v15, v15, v15 row_ror:2 row_mask:0xf bank_mask:0xf bound_ctrl:1
	ds_read_b128 v[104:107], v48 offset:22272
	s_nop 0
	v_add_f32_dpp v30, v15, v15 row_ror:1 row_mask:0xf bank_mask:0xf bound_ctrl:1
	v_pk_fma_f32 v[10:11], v[128:129], v[30:31], v[16:17] op_sel_hi:[1,0,1] neg_lo:[0,1,0] neg_hi:[0,1,0]
	v_pk_fma_f32 v[8:9], v[130:131], v[30:31], v[18:19] op_sel_hi:[1,0,1] neg_lo:[0,1,0] neg_hi:[0,1,0]
	v_pk_mul_f32 v[26:27], v[10:11], v[132:133] op_sel:[0,0] op_sel_hi:[0,1]
	v_pk_fma_f32 v[26:27], v[10:11], v[134:135], v[26:27] op_sel:[1,0,0] op_sel_hi:[1,1,1]
	v_pk_fma_f32 v[26:27], v[8:9], v[136:137], v[26:27] op_sel:[0,0,0] op_sel_hi:[0,1,1]
	v_pk_fma_f32 v[26:27], v[8:9], v[138:139], v[26:27] op_sel:[1,0,0] op_sel_hi:[1,1,1]
	s_waitcnt lgkmcnt(8)
	v_pk_fma_f32 v[16:17], v[76:77], v[160:161], v[10:11] op_sel_hi:[1,0,1]
	v_pk_fma_f32 v[18:19], v[78:79], v[160:161], v[8:9] op_sel_hi:[1,0,1]
	v_add_f32_dpp v15, v26, v26 row_ror:8 row_mask:0xf bank_mask:0xf bound_ctrl:1
	ds_read_b128 v[108:111], v48 offset:22528
	s_nop 0
	v_add_f32_dpp v15, v15, v15 row_ror:4 row_mask:0xf bank_mask:0xf bound_ctrl:1
	ds_read_b128 v[112:115], v48 offset:22784
	ds_read_b128 v[116:119], v48 offset:23040
	v_add_f32_dpp v15, v15, v15 row_ror:2 row_mask:0xf bank_mask:0xf bound_ctrl:1
	ds_read_b128 v[120:123], v48 offset:23296
	ds_write2st64_b32 v50, v25, v27 offset0:72 offset1:76
	v_add_f32_dpp v30, v15, v15 row_ror:1 row_mask:0xf bank_mask:0xf bound_ctrl:1
	s_waitcnt lgkmcnt(5)
	v_pk_fma_f32 v[10:11], v[80:81], v[30:31], v[16:17] op_sel_hi:[1,0,1] neg_lo:[0,1,0] neg_hi:[0,1,0]
	v_pk_fma_f32 v[8:9], v[82:83], v[30:31], v[18:19] op_sel_hi:[1,0,1] neg_lo:[0,1,0] neg_hi:[0,1,0]
	v_pk_mul_f32 v[24:25], v[10:11], v[84:85] op_sel:[0,0] op_sel_hi:[0,1]
	v_pk_fma_f32 v[24:25], v[10:11], v[86:87], v[24:25] op_sel:[1,0,0] op_sel_hi:[1,1,1]
	v_pk_fma_f32 v[24:25], v[8:9], v[88:89], v[24:25] op_sel:[0,0,0] op_sel_hi:[0,1,1]
	v_pk_fma_f32 v[24:25], v[8:9], v[90:91], v[24:25] op_sel:[1,0,0] op_sel_hi:[1,1,1]
	v_pk_fma_f32 v[16:17], v[92:93], v[160:161], v[10:11] op_sel:[0,1,0] op_sel_hi:[1,1,1]
	v_pk_fma_f32 v[18:19], v[94:95], v[160:161], v[8:9] op_sel:[0,1,0] op_sel_hi:[1,1,1]
	v_add_f32_dpp v15, v24, v24 row_ror:8 row_mask:0xf bank_mask:0xf bound_ctrl:1
	ds_read_b128 v[124:127], v48 offset:23552
	s_nop 0
	v_add_f32_dpp v15, v15, v15 row_ror:4 row_mask:0xf bank_mask:0xf bound_ctrl:1
	ds_read_b128 v[128:131], v48 offset:23808
	ds_read_b128 v[132:135], v48 offset:24064
	v_add_f32_dpp v15, v15, v15 row_ror:2 row_mask:0xf bank_mask:0xf bound_ctrl:1
	ds_read_b128 v[136:139], v48 offset:24320
	ds_read_b128 v[156:159], v49 offset:96
	v_add_f32_dpp v30, v15, v15 row_ror:1 row_mask:0xf bank_mask:0xf bound_ctrl:1
	v_pk_fma_f32 v[10:11], v[96:97], v[30:31], v[16:17] op_sel_hi:[1,0,1] neg_lo:[0,1,0] neg_hi:[0,1,0]
	v_pk_fma_f32 v[8:9], v[98:99], v[30:31], v[18:19] op_sel_hi:[1,0,1] neg_lo:[0,1,0] neg_hi:[0,1,0]
	v_pk_mul_f32 v[26:27], v[10:11], v[100:101] op_sel:[0,0] op_sel_hi:[0,1]
	v_pk_fma_f32 v[26:27], v[10:11], v[102:103], v[26:27] op_sel:[1,0,0] op_sel_hi:[1,1,1]
	v_pk_fma_f32 v[26:27], v[8:9], v[104:105], v[26:27] op_sel:[0,0,0] op_sel_hi:[0,1,1]
	v_pk_fma_f32 v[26:27], v[8:9], v[106:107], v[26:27] op_sel:[1,0,0] op_sel_hi:[1,1,1]
	s_waitcnt lgkmcnt(9)
	v_pk_fma_f32 v[16:17], v[108:109], v[162:163], v[10:11] op_sel_hi:[1,0,1]
	v_pk_fma_f32 v[18:19], v[110:111], v[162:163], v[8:9] op_sel_hi:[1,0,1]
	v_add_f32_dpp v15, v26, v26 row_ror:8 row_mask:0xf bank_mask:0xf bound_ctrl:1
	ds_read_b128 v[76:79], v48 offset:24576
	s_nop 0
	v_add_f32_dpp v15, v15, v15 row_ror:4 row_mask:0xf bank_mask:0xf bound_ctrl:1
	ds_read_b128 v[80:83], v48 offset:24832
	ds_read_b128 v[84:87], v48 offset:25088
	v_add_f32_dpp v15, v15, v15 row_ror:2 row_mask:0xf bank_mask:0xf bound_ctrl:1
	ds_read_b128 v[88:91], v48 offset:25344
	ds_write2st64_b32 v50, v25, v27 offset0:80 offset1:84
	v_add_f32_dpp v30, v15, v15 row_ror:1 row_mask:0xf bank_mask:0xf bound_ctrl:1
	s_waitcnt lgkmcnt(5)
	v_pk_fma_f32 v[10:11], v[112:113], v[30:31], v[16:17] op_sel_hi:[1,0,1] neg_lo:[0,1,0] neg_hi:[0,1,0]
	v_pk_fma_f32 v[8:9], v[114:115], v[30:31], v[18:19] op_sel_hi:[1,0,1] neg_lo:[0,1,0] neg_hi:[0,1,0]
	v_pk_mul_f32 v[24:25], v[10:11], v[116:117] op_sel:[0,0] op_sel_hi:[0,1]
	v_pk_fma_f32 v[24:25], v[10:11], v[118:119], v[24:25] op_sel:[1,0,0] op_sel_hi:[1,1,1]
	v_pk_fma_f32 v[24:25], v[8:9], v[120:121], v[24:25] op_sel:[0,0,0] op_sel_hi:[0,1,1]
	v_pk_fma_f32 v[24:25], v[8:9], v[122:123], v[24:25] op_sel:[1,0,0] op_sel_hi:[1,1,1]
	v_pk_fma_f32 v[16:17], v[124:125], v[162:163], v[10:11] op_sel:[0,1,0] op_sel_hi:[1,1,1]
	v_pk_fma_f32 v[18:19], v[126:127], v[162:163], v[8:9] op_sel:[0,1,0] op_sel_hi:[1,1,1]
	v_add_f32_dpp v15, v24, v24 row_ror:8 row_mask:0xf bank_mask:0xf bound_ctrl:1
	ds_read_b128 v[92:95], v48 offset:25600
	s_nop 0
	v_add_f32_dpp v15, v15, v15 row_ror:4 row_mask:0xf bank_mask:0xf bound_ctrl:1
	ds_read_b128 v[96:99], v48 offset:25856
	ds_read_b128 v[100:103], v48 offset:26112
	v_add_f32_dpp v15, v15, v15 row_ror:2 row_mask:0xf bank_mask:0xf bound_ctrl:1
	ds_read_b128 v[104:107], v48 offset:26368
	s_nop 0
	v_add_f32_dpp v30, v15, v15 row_ror:1 row_mask:0xf bank_mask:0xf bound_ctrl:1
	v_pk_fma_f32 v[10:11], v[128:129], v[30:31], v[16:17] op_sel_hi:[1,0,1] neg_lo:[0,1,0] neg_hi:[0,1,0]
	v_pk_fma_f32 v[8:9], v[130:131], v[30:31], v[18:19] op_sel_hi:[1,0,1] neg_lo:[0,1,0] neg_hi:[0,1,0]
	v_pk_mul_f32 v[26:27], v[10:11], v[132:133] op_sel:[0,0] op_sel_hi:[0,1]
	v_pk_fma_f32 v[26:27], v[10:11], v[134:135], v[26:27] op_sel:[1,0,0] op_sel_hi:[1,1,1]
	v_pk_fma_f32 v[26:27], v[8:9], v[136:137], v[26:27] op_sel:[0,0,0] op_sel_hi:[0,1,1]
	v_pk_fma_f32 v[26:27], v[8:9], v[138:139], v[26:27] op_sel:[1,0,0] op_sel_hi:[1,1,1]
	s_waitcnt lgkmcnt(8)
	v_pk_fma_f32 v[16:17], v[76:77], v[156:157], v[10:11] op_sel_hi:[1,0,1]
	v_pk_fma_f32 v[18:19], v[78:79], v[156:157], v[8:9] op_sel_hi:[1,0,1]
	v_add_f32_dpp v15, v26, v26 row_ror:8 row_mask:0xf bank_mask:0xf bound_ctrl:1
	ds_read_b128 v[108:111], v48 offset:26624
	s_nop 0
	v_add_f32_dpp v15, v15, v15 row_ror:4 row_mask:0xf bank_mask:0xf bound_ctrl:1
	ds_read_b128 v[112:115], v48 offset:26880
	ds_read_b128 v[116:119], v48 offset:27136
	v_add_f32_dpp v15, v15, v15 row_ror:2 row_mask:0xf bank_mask:0xf bound_ctrl:1
	ds_read_b128 v[120:123], v48 offset:27392
	ds_write2st64_b32 v50, v25, v27 offset0:88 offset1:92
	v_add_f32_dpp v30, v15, v15 row_ror:1 row_mask:0xf bank_mask:0xf bound_ctrl:1
	s_waitcnt lgkmcnt(5)
	v_pk_fma_f32 v[10:11], v[80:81], v[30:31], v[16:17] op_sel_hi:[1,0,1] neg_lo:[0,1,0] neg_hi:[0,1,0]
	v_pk_fma_f32 v[8:9], v[82:83], v[30:31], v[18:19] op_sel_hi:[1,0,1] neg_lo:[0,1,0] neg_hi:[0,1,0]
	v_pk_mul_f32 v[24:25], v[10:11], v[84:85] op_sel:[0,0] op_sel_hi:[0,1]
	v_pk_fma_f32 v[24:25], v[10:11], v[86:87], v[24:25] op_sel:[1,0,0] op_sel_hi:[1,1,1]
	v_pk_fma_f32 v[24:25], v[8:9], v[88:89], v[24:25] op_sel:[0,0,0] op_sel_hi:[0,1,1]
	v_pk_fma_f32 v[24:25], v[8:9], v[90:91], v[24:25] op_sel:[1,0,0] op_sel_hi:[1,1,1]
	v_pk_fma_f32 v[16:17], v[92:93], v[156:157], v[10:11] op_sel:[0,1,0] op_sel_hi:[1,1,1]
	v_pk_fma_f32 v[18:19], v[94:95], v[156:157], v[8:9] op_sel:[0,1,0] op_sel_hi:[1,1,1]
	v_add_f32_dpp v15, v24, v24 row_ror:8 row_mask:0xf bank_mask:0xf bound_ctrl:1
	ds_read_b128 v[124:127], v48 offset:27648
	s_nop 0
	v_add_f32_dpp v15, v15, v15 row_ror:4 row_mask:0xf bank_mask:0xf bound_ctrl:1
	ds_read_b128 v[128:131], v48 offset:27904
	ds_read_b128 v[132:135], v48 offset:28160
	v_add_f32_dpp v15, v15, v15 row_ror:2 row_mask:0xf bank_mask:0xf bound_ctrl:1
	ds_read_b128 v[136:139], v48 offset:28416
	ds_read_b128 v[160:163], v49 offset:112
	v_add_f32_dpp v30, v15, v15 row_ror:1 row_mask:0xf bank_mask:0xf bound_ctrl:1
	v_pk_fma_f32 v[10:11], v[96:97], v[30:31], v[16:17] op_sel_hi:[1,0,1] neg_lo:[0,1,0] neg_hi:[0,1,0]
	v_pk_fma_f32 v[8:9], v[98:99], v[30:31], v[18:19] op_sel_hi:[1,0,1] neg_lo:[0,1,0] neg_hi:[0,1,0]
	v_pk_mul_f32 v[26:27], v[10:11], v[100:101] op_sel:[0,0] op_sel_hi:[0,1]
	v_pk_fma_f32 v[26:27], v[10:11], v[102:103], v[26:27] op_sel:[1,0,0] op_sel_hi:[1,1,1]
	v_pk_fma_f32 v[26:27], v[8:9], v[104:105], v[26:27] op_sel:[0,0,0] op_sel_hi:[0,1,1]
	v_pk_fma_f32 v[26:27], v[8:9], v[106:107], v[26:27] op_sel:[1,0,0] op_sel_hi:[1,1,1]
	s_waitcnt lgkmcnt(9)
	v_pk_fma_f32 v[16:17], v[108:109], v[158:159], v[10:11] op_sel_hi:[1,0,1]
	v_pk_fma_f32 v[18:19], v[110:111], v[158:159], v[8:9] op_sel_hi:[1,0,1]
	v_add_f32_dpp v15, v26, v26 row_ror:8 row_mask:0xf bank_mask:0xf bound_ctrl:1
	ds_read_b128 v[76:79], v48 offset:28672
	s_nop 0
	v_add_f32_dpp v15, v15, v15 row_ror:4 row_mask:0xf bank_mask:0xf bound_ctrl:1
	ds_read_b128 v[80:83], v48 offset:28928
	ds_read_b128 v[84:87], v48 offset:29184
	v_add_f32_dpp v15, v15, v15 row_ror:2 row_mask:0xf bank_mask:0xf bound_ctrl:1
	ds_read_b128 v[88:91], v48 offset:29440
	ds_write2st64_b32 v50, v25, v27 offset0:96 offset1:100
	v_add_f32_dpp v30, v15, v15 row_ror:1 row_mask:0xf bank_mask:0xf bound_ctrl:1
	ds_read_b128 v[56:59], v52
	s_waitcnt lgkmcnt(6)
	v_pk_fma_f32 v[10:11], v[112:113], v[30:31], v[16:17] op_sel_hi:[1,0,1] neg_lo:[0,1,0] neg_hi:[0,1,0]
	v_pk_fma_f32 v[8:9], v[114:115], v[30:31], v[18:19] op_sel_hi:[1,0,1] neg_lo:[0,1,0] neg_hi:[0,1,0]
	v_pk_mul_f32 v[24:25], v[10:11], v[116:117] op_sel:[0,0] op_sel_hi:[0,1]
	v_pk_fma_f32 v[24:25], v[10:11], v[118:119], v[24:25] op_sel:[1,0,0] op_sel_hi:[1,1,1]
	v_pk_fma_f32 v[24:25], v[8:9], v[120:121], v[24:25] op_sel:[0,0,0] op_sel_hi:[0,1,1]
	v_pk_fma_f32 v[24:25], v[8:9], v[122:123], v[24:25] op_sel:[1,0,0] op_sel_hi:[1,1,1]
	v_pk_fma_f32 v[16:17], v[124:125], v[158:159], v[10:11] op_sel:[0,1,0] op_sel_hi:[1,1,1]
	v_pk_fma_f32 v[18:19], v[126:127], v[158:159], v[8:9] op_sel:[0,1,0] op_sel_hi:[1,1,1]
	v_add_f32_dpp v15, v24, v24 row_ror:8 row_mask:0xf bank_mask:0xf bound_ctrl:1
	ds_read_b128 v[92:95], v48 offset:29696
	s_nop 0
	v_add_f32_dpp v15, v15, v15 row_ror:4 row_mask:0xf bank_mask:0xf bound_ctrl:1
	ds_read_b128 v[96:99], v48 offset:29952
	ds_read_b128 v[100:103], v48 offset:30208
	v_add_f32_dpp v15, v15, v15 row_ror:2 row_mask:0xf bank_mask:0xf bound_ctrl:1
	ds_read_b128 v[104:107], v48 offset:30464
	s_nop 0
	v_add_f32_dpp v30, v15, v15 row_ror:1 row_mask:0xf bank_mask:0xf bound_ctrl:1
	s_waitcnt lgkmcnt(4)
	v_min_u32_e32 v56, v56, v57
	v_min3_u32 v56, v56, v58, v59
	v_pk_fma_f32 v[10:11], v[128:129], v[30:31], v[16:17] op_sel_hi:[1,0,1] neg_lo:[0,1,0] neg_hi:[0,1,0]
	v_pk_fma_f32 v[8:9], v[130:131], v[30:31], v[18:19] op_sel_hi:[1,0,1] neg_lo:[0,1,0] neg_hi:[0,1,0]
	v_pk_mul_f32 v[26:27], v[10:11], v[132:133] op_sel:[0,0] op_sel_hi:[0,1]
	v_pk_fma_f32 v[26:27], v[10:11], v[134:135], v[26:27] op_sel:[1,0,0] op_sel_hi:[1,1,1]
	v_pk_fma_f32 v[26:27], v[8:9], v[136:137], v[26:27] op_sel:[0,0,0] op_sel_hi:[0,1,1]
	v_pk_fma_f32 v[26:27], v[8:9], v[138:139], v[26:27] op_sel:[1,0,0] op_sel_hi:[1,1,1]
	v_pk_fma_f32 v[16:17], v[76:77], v[160:161], v[10:11] op_sel_hi:[1,0,1]
	v_pk_fma_f32 v[18:19], v[78:79], v[160:161], v[8:9] op_sel_hi:[1,0,1]
	v_add_f32_dpp v15, v26, v26 row_ror:8 row_mask:0xf bank_mask:0xf bound_ctrl:1
	ds_read_b128 v[108:111], v48 offset:30720
	s_nop 0
	v_add_f32_dpp v15, v15, v15 row_ror:4 row_mask:0xf bank_mask:0xf bound_ctrl:1
	ds_read_b128 v[112:115], v48 offset:30976
	ds_read_b128 v[116:119], v48 offset:31232
	v_add_f32_dpp v15, v15, v15 row_ror:2 row_mask:0xf bank_mask:0xf bound_ctrl:1
	ds_read_b128 v[120:123], v48 offset:31488
	ds_read_b128 v[140:143], v48 offset:34560
	ds_write2st64_b32 v50, v25, v27 offset0:104 offset1:108
	v_add_f32_dpp v30, v15, v15 row_ror:1 row_mask:0xf bank_mask:0xf bound_ctrl:1
	s_waitcnt lgkmcnt(6)
	v_pk_fma_f32 v[10:11], v[80:81], v[30:31], v[16:17] op_sel_hi:[1,0,1] neg_lo:[0,1,0] neg_hi:[0,1,0]
	v_pk_fma_f32 v[8:9], v[82:83], v[30:31], v[18:19] op_sel_hi:[1,0,1] neg_lo:[0,1,0] neg_hi:[0,1,0]
	v_pk_mul_f32 v[24:25], v[10:11], v[84:85] op_sel:[0,0] op_sel_hi:[0,1]
	v_pk_fma_f32 v[24:25], v[10:11], v[86:87], v[24:25] op_sel:[1,0,0] op_sel_hi:[1,1,1]
	v_pk_fma_f32 v[24:25], v[8:9], v[88:89], v[24:25] op_sel:[0,0,0] op_sel_hi:[0,1,1]
	v_pk_fma_f32 v[24:25], v[8:9], v[90:91], v[24:25] op_sel:[1,0,0] op_sel_hi:[1,1,1]
	v_pk_fma_f32 v[16:17], v[92:93], v[160:161], v[10:11] op_sel:[0,1,0] op_sel_hi:[1,1,1]
	v_pk_fma_f32 v[18:19], v[94:95], v[160:161], v[8:9] op_sel:[0,1,0] op_sel_hi:[1,1,1]
	v_add_f32_dpp v15, v24, v24 row_ror:8 row_mask:0xf bank_mask:0xf bound_ctrl:1
	ds_read_b128 v[124:127], v48 offset:31744
	s_nop 0
	v_add_f32_dpp v15, v15, v15 row_ror:4 row_mask:0xf bank_mask:0xf bound_ctrl:1
	ds_read_b128 v[128:131], v48 offset:32000
	ds_read_b128 v[132:135], v48 offset:32256
	v_add_f32_dpp v15, v15, v15 row_ror:2 row_mask:0xf bank_mask:0xf bound_ctrl:1
	ds_read_b128 v[136:139], v48 offset:32512
	s_nop 0
	v_add_f32_dpp v30, v15, v15 row_ror:1 row_mask:0xf bank_mask:0xf bound_ctrl:1
	v_readfirstlane_b32 s54, v56
	s_add_u32 s64, s6, 2
	s_cmp_lt_u32 s54, s64
	s_cbranch_scc1 .Lss_spin_1
.Lss_ok_1:
	v_pk_fma_f32 v[10:11], v[96:97], v[30:31], v[16:17] op_sel_hi:[1,0,1] neg_lo:[0,1,0] neg_hi:[0,1,0]
	v_pk_fma_f32 v[8:9], v[98:99], v[30:31], v[18:19] op_sel_hi:[1,0,1] neg_lo:[0,1,0] neg_hi:[0,1,0]
	v_pk_mul_f32 v[26:27], v[10:11], v[100:101] op_sel:[0,0] op_sel_hi:[0,1]
	v_pk_fma_f32 v[26:27], v[10:11], v[102:103], v[26:27] op_sel:[1,0,0] op_sel_hi:[1,1,1]
	v_pk_fma_f32 v[26:27], v[8:9], v[104:105], v[26:27] op_sel:[0,0,0] op_sel_hi:[0,1,1]
	v_pk_fma_f32 v[26:27], v[8:9], v[106:107], v[26:27] op_sel:[1,0,0] op_sel_hi:[1,1,1]
	s_waitcnt lgkmcnt(9)
	v_pk_fma_f32 v[16:17], v[108:109], v[162:163], v[10:11] op_sel_hi:[1,0,1]
	v_pk_fma_f32 v[18:19], v[110:111], v[162:163], v[8:9] op_sel_hi:[1,0,1]
	v_add_f32_dpp v15, v26, v26 row_ror:8 row_mask:0xf bank_mask:0xf bound_ctrl:1
	ds_read_b128 v[76:79], v34 offset:0
	s_nop 0
	v_add_f32_dpp v15, v15, v15 row_ror:4 row_mask:0xf bank_mask:0xf bound_ctrl:1
	ds_read_b128 v[80:83], v34 offset:256
	ds_read_b128 v[84:87], v34 offset:512
	v_add_f32_dpp v15, v15, v15 row_ror:2 row_mask:0xf bank_mask:0xf bound_ctrl:1
	ds_read_b128 v[88:91], v34 offset:768
	ds_read_b128 v[144:147], v34 offset:32768
	ds_write2st64_b32 v50, v25, v27 offset0:112 offset1:116
	v_add_f32_dpp v30, v15, v15 row_ror:1 row_mask:0xf bank_mask:0xf bound_ctrl:1
	ds_read_b128 v[156:159], v35 offset:0
	s_waitcnt lgkmcnt(7)
	v_pk_fma_f32 v[10:11], v[112:113], v[30:31], v[16:17] op_sel_hi:[1,0,1] neg_lo:[0,1,0] neg_hi:[0,1,0]
	v_pk_fma_f32 v[8:9], v[114:115], v[30:31], v[18:19] op_sel_hi:[1,0,1] neg_lo:[0,1,0] neg_hi:[0,1,0]
	v_pk_mul_f32 v[24:25], v[10:11], v[116:117] op_sel:[0,0] op_sel_hi:[0,1]
	v_pk_fma_f32 v[24:25], v[10:11], v[118:119], v[24:25] op_sel:[1,0,0] op_sel_hi:[1,1,1]
	v_pk_fma_f32 v[24:25], v[8:9], v[120:121], v[24:25] op_sel:[0,0,0] op_sel_hi:[0,1,1]
	v_pk_fma_f32 v[24:25], v[8:9], v[122:123], v[24:25] op_sel:[1,0,0] op_sel_hi:[1,1,1]
	v_pk_fma_f32 v[16:17], v[124:125], v[162:163], v[10:11] op_sel:[0,1,0] op_sel_hi:[1,1,1]
	v_pk_fma_f32 v[18:19], v[126:127], v[162:163], v[8:9] op_sel:[0,1,0] op_sel_hi:[1,1,1]
	v_add_f32_dpp v15, v24, v24 row_ror:8 row_mask:0xf bank_mask:0xf bound_ctrl:1
	ds_read_b128 v[92:95], v34 offset:1024
	s_nop 0
	v_add_f32_dpp v15, v15, v15 row_ror:4 row_mask:0xf bank_mask:0xf bound_ctrl:1
	ds_read_b128 v[96:99], v34 offset:1280
	ds_read_b128 v[100:103], v34 offset:1536
	v_add_f32_dpp v15, v15, v15 row_ror:2 row_mask:0xf bank_mask:0xf bound_ctrl:1
	ds_read_b128 v[104:107], v34 offset:1792
	s_nop 0
	v_add_f32_dpp v30, v15, v15 row_ror:1 row_mask:0xf bank_mask:0xf bound_ctrl:1
	v_pk_fma_f32 v[10:11], v[128:129], v[30:31], v[16:17] op_sel_hi:[1,0,1] neg_lo:[0,1,0] neg_hi:[0,1,0]
	v_pk_fma_f32 v[8:9], v[130:131], v[30:31], v[18:19] op_sel_hi:[1,0,1] neg_lo:[0,1,0] neg_hi:[0,1,0]
	v_pk_mul_f32 v[26:27], v[10:11], v[132:133] op_sel:[0,0] op_sel_hi:[0,1]
	v_pk_fma_f32 v[26:27], v[10:11], v[134:135], v[26:27] op_sel:[1,0,0] op_sel_hi:[1,1,1]
	v_pk_fma_f32 v[26:27], v[8:9], v[136:137], v[26:27] op_sel:[0,0,0] op_sel_hi:[0,1,1]
	v_pk_fma_f32 v[26:27], v[8:9], v[138:139], v[26:27] op_sel:[1,0,0] op_sel_hi:[1,1,1]
	ds_write2st64_b32 v50, v25, v27 offset0:120 offset1:124
	v_pk_mul_f32 v[10:11], v[10:11], v[140:141]
	v_pk_mul_f32 v[8:9], v[8:9], v[142:143]
	s_waitcnt lgkmcnt(7)
	v_pk_mul_f32 v[24:25], v[10:11], v[144:145]
	v_pk_fma_f32 v[24:25], v[8:9], v[146:147], v[24:25]
	v_add_f32_e32 v24, v24, v25
	s_waitcnt lgkmcnt(5)
	v_pk_fma_f32 v[16:17], v[76:77], v[156:157], v[10:11] op_sel_hi:[1,0,1]
	v_pk_fma_f32 v[18:19], v[78:79], v[156:157], v[8:9] op_sel_hi:[1,0,1]
	v_add_f32_dpp v15, v24, v24 row_ror:8 row_mask:0xf bank_mask:0xf bound_ctrl:1
	v_add_u32_e32 v51, 1, v51
	s_add_u32 s6, s6, 1
	v_add_f32_dpp v15, v15, v15 row_ror:4 row_mask:0xf bank_mask:0xf bound_ctrl:1
	ds_write_b32 v53, v51
	ds_read_b128 v[108:111], v34 offset:2048
	v_add_f32_dpp v15, v15, v15 row_ror:2 row_mask:0xf bank_mask:0xf bound_ctrl:1
	ds_read_b128 v[112:115], v34 offset:2304
	ds_read_b128 v[116:119], v34 offset:2560
	v_add_f32_dpp v30, v15, v15 row_ror:1 row_mask:0xf bank_mask:0xf bound_ctrl:1
	ds_read_b128 v[120:123], v34 offset:2816
	s_cmp_lt_u32 s6, 0x100
	s_cbranch_scc1 .Lsc_S_loop
	s_waitcnt lgkmcnt(0)
	s_branch .Lsc_item_end
	s_nop 0
	s_nop 0
	s_nop 0
	s_nop 0
	s_nop 0
	s_nop 0
	s_nop 0
	s_nop 0
	s_nop 0
	s_nop 0
	s_nop 0
	s_nop 0
	s_nop 0
	s_nop 0
	s_nop 0
	s_nop 0
	s_nop 0
